# v86 with OUT0/OUT1 also as one hand-written 256x256 tile per workgroup on the 256-workgroup path (instead of two 256x128 hand tiles)
# speedup vs baseline: 1.1231x; 1.0125x over previous
.LBB0_178:
	s_andn2_b64 vcc, exec, s[28:29]
	s_cbranch_vccnz .LBB0_194
	v_readlane_b32 s24, v236, 3
	v_readlane_b32 s25, v236, 4
	s_andn2_b64 vcc, exec, s[24:25]
	s_cbranch_vccnz .LBB0_743
	s_add_u32 s26, s44, 0xfa0b600
	s_addc_u32 s27, s45, 0
	v_readlane_b32 s24, v235, 43
	v_readlane_b32 s25, v236, 5
	v_readlane_b32 s34, v236, 9
	s_lshr_b32 s28, s34, 2
	s_lshl_b32 s28, s28, 3
	s_and_b32 s34, s34, 3
	s_lshl_b32 s34, s34, 1
	s_or_b32 s34, s34, s28
	s_branch .LBB0_182
.LBB0_182:
	s_and_b32 s36, s34, 56
	s_or_b32 s36, s36, s83
	s_lshl_b32 s36, s36, 8
	s_and_b32 s35, s34, 7
	s_lshl_b32 s35, s35, 7
	s_lshl_b32 s54, s36, 11
	s_add_u32 s28, s50, s54
	s_addc_u32 s29, s51, 0
	s_lshl_b32 s54, s35, 11
	s_add_u32 s30, s48, s54
	s_addc_u32 s31, s49, 0
	v_readfirstlane_b32 s54, v200
	s_lshr_b32 s54, s54, 6
	s_lshl_b32 s32, s54, 11
	s_add_u32 s32, s32, 16
	s_lshl_b32 s54, s54, 16
	s_add_u32 s28, s28, s54
	s_addc_u32 s29, s29, 0
	s_add_u32 s30, s30, s54
	s_addc_u32 s31, s31, 0
	v_bfe_u32 v173, v200, 4, 2
	v_sub_u32_e32 v173, 0, v173
	v_and_b32_e32 v173, 3, v173
	v_and_b32_e32 v172, 3, v200
	v_xor_b32_e32 v172, v172, v173
	v_bfe_u32 v173, v200, 2, 4
	v_lshlrev_b32_e32 v173, 11, v173
	v_lshl_or_b32 v170, v172, 4, v173
	v_add_u32_e32 v171, 0x8000, v170
	v_bfe_u32 v172, v200, 2, 2
	v_sub_u32_e32 v172, 0, v172
	v_and_b32_e32 v172, 3, v172
	v_bfe_u32 v173, v200, 4, 2
	v_xor_b32_e32 v172, v172, v173
	v_and_b32_e32 v173, 15, v200
	v_bfe_u32 v174, v200, 8, 1
	v_lshl_or_b32 v174, v174, 7, v173
	v_lshlrev_b32_e32 v174, 6, v174
	v_lshl_or_b32 v164, v172, 4, v174
	v_bfe_u32 v174, v200, 6, 2
	v_lshl_or_b32 v174, v174, 6, v173
	v_lshlrev_b32_e32 v174, 6, v174
	v_lshl_or_b32 v165, v172, 4, v174
	v_add_u32_e32 v165, 0x4000, v165
	v_bfe_u32 v172, v200, 6, 2
	v_bfe_u32 v173, v200, 4, 2
	v_lshlrev_b32_e32 v172, 6, v172
	v_lshl_or_b32 v172, v173, 2, v172
	v_add_u32_e32 v172, s35, v172
	v_lshlrev_b32_e32 v172, 2, v172
	global_load_dwordx4 v[132:135], v172, s[42:43]
	global_load_dwordx4 v[136:139], v172, s[42:43] offset:64
	global_load_dwordx4 v[140:143], v172, s[42:43] offset:128
	global_load_dwordx4 v[144:147], v172, s[42:43] offset:192
	s_mov_b32 s52, s32
	s_mov_b32 m0, s52
	s_nop 0
	global_load_lds_dwordx4 v170, s[28:29]
	s_add_u32 m0, s52, 0x400
	s_nop 0
	global_load_lds_dwordx4 v171, s[28:29]
	s_add_u32 m0, s52, 0x4000
	s_nop 0
	global_load_lds_dwordx4 v170, s[30:31]
	s_add_u32 m0, s52, 0x4400
	s_nop 0
	global_load_lds_dwordx4 v171, s[30:31]
	s_add_u32 s28, s28, 64
	s_addc_u32 s29, s29, 0
	s_add_u32 s30, s30, 64
	s_addc_u32 s31, s31, 0
	s_add_u32 s52, s32, 0x8000
	s_mov_b32 m0, s52
	s_nop 0
	global_load_lds_dwordx4 v170, s[28:29]
	s_add_u32 m0, s52, 0x400
	s_nop 0
	global_load_lds_dwordx4 v171, s[28:29]
	s_add_u32 m0, s52, 0x4000
	s_nop 0
	global_load_lds_dwordx4 v170, s[30:31]
	s_add_u32 m0, s52, 0x4400
	s_nop 0
	global_load_lds_dwordx4 v171, s[30:31]
	s_add_u32 s28, s28, 64
	s_addc_u32 s29, s29, 0
	s_add_u32 s30, s30, 64
	s_addc_u32 s31, s31, 0
	s_add_u32 s52, s32, 0x10000
	s_mov_b32 m0, s52
	s_nop 0
	global_load_lds_dwordx4 v170, s[28:29]
	s_add_u32 m0, s52, 0x400
	s_nop 0
	global_load_lds_dwordx4 v171, s[28:29]
	s_add_u32 m0, s52, 0x4000
	s_nop 0
	global_load_lds_dwordx4 v170, s[30:31]
	s_add_u32 m0, s52, 0x4400
	s_nop 0
	global_load_lds_dwordx4 v171, s[30:31]
	s_add_u32 s28, s28, 64
	s_addc_u32 s29, s29, 0
	s_add_u32 s30, s30, 64
	s_addc_u32 s31, s31, 0
	s_add_u32 s52, s32, 0x18000
	s_mov_b32 m0, s52
	s_nop 0
	global_load_lds_dwordx4 v170, s[28:29]
	s_add_u32 m0, s52, 0x400
	s_nop 0
	global_load_lds_dwordx4 v171, s[28:29]
	s_add_u32 m0, s52, 0x4000
	s_nop 0
	global_load_lds_dwordx4 v170, s[30:31]
	s_add_u32 m0, s52, 0x4400
	s_nop 0
	global_load_lds_dwordx4 v171, s[30:31]
	s_add_u32 s28, s28, 64
	s_addc_u32 s29, s29, 0
	s_add_u32 s30, s30, 64
	s_addc_u32 s31, s31, 0
	s_waitcnt vmcnt(16)
	v_mov_b32_e32 v4, v132
	v_mov_b32_e32 v5, v133
	v_mov_b32_e32 v6, v134
	v_mov_b32_e32 v7, v135
	v_mov_b32_e32 v8, v136
	v_mov_b32_e32 v9, v137
	v_mov_b32_e32 v10, v138
	v_mov_b32_e32 v11, v139
	v_mov_b32_e32 v12, v140
	v_mov_b32_e32 v13, v141
	v_mov_b32_e32 v14, v142
	v_mov_b32_e32 v15, v143
	v_mov_b32_e32 v16, v144
	v_mov_b32_e32 v17, v145
	v_mov_b32_e32 v18, v146
	v_mov_b32_e32 v19, v147
	v_mov_b32_e32 v20, v132
	v_mov_b32_e32 v21, v133
	v_mov_b32_e32 v22, v134
	v_mov_b32_e32 v23, v135
	v_mov_b32_e32 v24, v136
	v_mov_b32_e32 v25, v137
	v_mov_b32_e32 v26, v138
	v_mov_b32_e32 v27, v139
	v_mov_b32_e32 v28, v140
	v_mov_b32_e32 v29, v141
	v_mov_b32_e32 v30, v142
	v_mov_b32_e32 v31, v143
	v_mov_b32_e32 v32, v144
	v_mov_b32_e32 v33, v145
	v_mov_b32_e32 v34, v146
	v_mov_b32_e32 v35, v147
	v_mov_b32_e32 v36, v132
	v_mov_b32_e32 v37, v133
	v_mov_b32_e32 v38, v134
	v_mov_b32_e32 v39, v135
	v_mov_b32_e32 v40, v136
	v_mov_b32_e32 v41, v137
	v_mov_b32_e32 v42, v138
	v_mov_b32_e32 v43, v139
	v_mov_b32_e32 v44, v140
	v_mov_b32_e32 v45, v141
	v_mov_b32_e32 v46, v142
	v_mov_b32_e32 v47, v143
	v_mov_b32_e32 v48, v144
	v_mov_b32_e32 v49, v145
	v_mov_b32_e32 v50, v146
	v_mov_b32_e32 v51, v147
	v_mov_b32_e32 v52, v132
	v_mov_b32_e32 v53, v133
	v_mov_b32_e32 v54, v134
	v_mov_b32_e32 v55, v135
	v_mov_b32_e32 v56, v136
	v_mov_b32_e32 v57, v137
	v_mov_b32_e32 v58, v138
	v_mov_b32_e32 v59, v139
	v_mov_b32_e32 v60, v140
	v_mov_b32_e32 v61, v141
	v_mov_b32_e32 v62, v142
	v_mov_b32_e32 v63, v143
	v_mov_b32_e32 v64, v144
	v_mov_b32_e32 v65, v145
	v_mov_b32_e32 v66, v146
	v_mov_b32_e32 v67, v147
	v_mov_b32_e32 v68, v132
	v_mov_b32_e32 v69, v133
	v_mov_b32_e32 v70, v134
	v_mov_b32_e32 v71, v135
	v_mov_b32_e32 v72, v136
	v_mov_b32_e32 v73, v137
	v_mov_b32_e32 v74, v138
	v_mov_b32_e32 v75, v139
	v_mov_b32_e32 v76, v140
	v_mov_b32_e32 v77, v141
	v_mov_b32_e32 v78, v142
	v_mov_b32_e32 v79, v143
	v_mov_b32_e32 v80, v144
	v_mov_b32_e32 v81, v145
	v_mov_b32_e32 v82, v146
	v_mov_b32_e32 v83, v147
	v_mov_b32_e32 v84, v132
	v_mov_b32_e32 v85, v133
	v_mov_b32_e32 v86, v134
	v_mov_b32_e32 v87, v135
	v_mov_b32_e32 v88, v136
	v_mov_b32_e32 v89, v137
	v_mov_b32_e32 v90, v138
	v_mov_b32_e32 v91, v139
	v_mov_b32_e32 v92, v140
	v_mov_b32_e32 v93, v141
	v_mov_b32_e32 v94, v142
	v_mov_b32_e32 v95, v143
	v_mov_b32_e32 v96, v144
	v_mov_b32_e32 v97, v145
	v_mov_b32_e32 v98, v146
	v_mov_b32_e32 v99, v147
	v_mov_b32_e32 v100, v132
	v_mov_b32_e32 v101, v133
	v_mov_b32_e32 v102, v134
	v_mov_b32_e32 v103, v135
	v_mov_b32_e32 v104, v136
	v_mov_b32_e32 v105, v137
	v_mov_b32_e32 v106, v138
	v_mov_b32_e32 v107, v139
	v_mov_b32_e32 v108, v140
	v_mov_b32_e32 v109, v141
	v_mov_b32_e32 v110, v142
	v_mov_b32_e32 v111, v143
	v_mov_b32_e32 v112, v144
	v_mov_b32_e32 v113, v145
	v_mov_b32_e32 v114, v146
	v_mov_b32_e32 v115, v147
	v_mov_b32_e32 v116, v132
	v_mov_b32_e32 v117, v133
	v_mov_b32_e32 v118, v134
	v_mov_b32_e32 v119, v135
	v_mov_b32_e32 v120, v136
	v_mov_b32_e32 v121, v137
	v_mov_b32_e32 v122, v138
	v_mov_b32_e32 v123, v139
	v_mov_b32_e32 v124, v140
	v_mov_b32_e32 v125, v141
	v_mov_b32_e32 v126, v142
	v_mov_b32_e32 v127, v143
	v_mov_b32_e32 v128, v144
	v_mov_b32_e32 v129, v145
	v_mov_b32_e32 v130, v146
	v_mov_b32_e32 v131, v147
	s_waitcnt vmcnt(12)
	s_barrier
	s_mov_b32 s37, 0
	s_mov_b32 s53, 0
	s_nop 1
	v_add_u32_e32 v168, s37, v165
	v_add_u32_e32 v169, s37, v164
	ds_read_b128 v[132:135], v168 offset:16
	ds_read_b128 v[136:139], v168 offset:1040
	ds_read_b128 v[140:143], v168 offset:2064
	ds_read_b128 v[144:147], v168 offset:3088
	ds_read_b128 v[184:187], v169 offset:16
	ds_read_b128 v[188:191], v169 offset:1040
	ds_read_b128 v[192:195], v169 offset:2064
	ds_read_b128 v[196:199], v169 offset:3088
	s_waitcnt lgkmcnt(0)
.Lt_out1:
	v_add_u32_e32 v169, s37, v164
	v_mfma_f32_16x16x32_f16 v[4:7], v[132:135], v[184:187], v[4:7]
	ds_read_b128 v[238:241], v169 offset:4112
	v_mfma_f32_16x16x32_f16 v[8:11], v[136:139], v[184:187], v[8:11]
	ds_read_b128 v[242:245], v169 offset:5136
	v_mfma_f32_16x16x32_f16 v[12:15], v[140:143], v[184:187], v[12:15]
	ds_read_b128 v[246:249], v169 offset:6160
	v_mfma_f32_16x16x32_f16 v[16:19], v[144:147], v[184:187], v[16:19]
	ds_read_b128 v[250:253], v169 offset:7184
	v_mfma_f32_16x16x32_f16 v[20:23], v[132:135], v[188:191], v[20:23]
	v_mfma_f32_16x16x32_f16 v[24:27], v[136:139], v[188:191], v[24:27]
	v_mfma_f32_16x16x32_f16 v[28:31], v[140:143], v[188:191], v[28:31]
	v_mfma_f32_16x16x32_f16 v[32:35], v[144:147], v[188:191], v[32:35]
	v_mfma_f32_16x16x32_f16 v[36:39], v[132:135], v[192:195], v[36:39]
	v_mfma_f32_16x16x32_f16 v[40:43], v[136:139], v[192:195], v[40:43]
	v_mfma_f32_16x16x32_f16 v[44:47], v[140:143], v[192:195], v[44:47]
	v_mfma_f32_16x16x32_f16 v[48:51], v[144:147], v[192:195], v[48:51]
	v_mfma_f32_16x16x32_f16 v[52:55], v[132:135], v[196:199], v[52:55]
	v_mfma_f32_16x16x32_f16 v[56:59], v[136:139], v[196:199], v[56:59]
	v_mfma_f32_16x16x32_f16 v[60:63], v[140:143], v[196:199], v[60:63]
	v_mfma_f32_16x16x32_f16 v[64:67], v[144:147], v[196:199], v[64:67]
	s_waitcnt vmcnt(8) lgkmcnt(0)
	s_barrier
	s_add_i32 s52, s37, 0x8000
	s_cmp_lg_u32 s37, 0x18000
	s_cselect_b32 s52, s52, 0
	v_add_u32_e32 v168, s52, v165
	v_add_u32_e32 v169, s52, v164
	s_add_u32 vcc_lo, s32, s37
	v_mfma_f32_16x16x32_f16 v[68:71], v[132:135], v[238:241], v[68:71]
	ds_read_b128 v[148:151], v168 offset:16
	ds_read_b128 v[184:187], v169 offset:16
	v_mfma_f32_16x16x32_f16 v[72:75], v[136:139], v[238:241], v[72:75]
	ds_read_b128 v[152:155], v168 offset:1040
	ds_read_b128 v[188:191], v169 offset:1040
	v_mfma_f32_16x16x32_f16 v[76:79], v[140:143], v[238:241], v[76:79]
	ds_read_b128 v[156:159], v168 offset:2064
	ds_read_b128 v[192:195], v169 offset:2064
	v_mfma_f32_16x16x32_f16 v[80:83], v[144:147], v[238:241], v[80:83]
	ds_read_b128 v[160:163], v168 offset:3088
	ds_read_b128 v[196:199], v169 offset:3088
	v_mfma_f32_16x16x32_f16 v[84:87], v[132:135], v[242:245], v[84:87]
	v_mfma_f32_16x16x32_f16 v[88:91], v[136:139], v[242:245], v[88:91]
	v_mfma_f32_16x16x32_f16 v[92:95], v[140:143], v[242:245], v[92:95]
	v_mfma_f32_16x16x32_f16 v[96:99], v[144:147], v[242:245], v[96:99]
	v_mfma_f32_16x16x32_f16 v[100:103], v[132:135], v[246:249], v[100:103]
	s_mov_b32 m0, vcc_lo
	s_nop 0
	global_load_lds_dwordx4 v170, s[28:29]
	v_mfma_f32_16x16x32_f16 v[104:107], v[136:139], v[246:249], v[104:107]
	s_add_u32 m0, vcc_lo, 0x400
	s_nop 0
	global_load_lds_dwordx4 v171, s[28:29]
	v_mfma_f32_16x16x32_f16 v[108:111], v[140:143], v[246:249], v[108:111]
	s_add_u32 m0, vcc_lo, 0x4000
	s_nop 0
	global_load_lds_dwordx4 v170, s[30:31]
	v_mfma_f32_16x16x32_f16 v[112:115], v[144:147], v[246:249], v[112:115]
	s_add_u32 m0, vcc_lo, 0x4400
	s_nop 0
	global_load_lds_dwordx4 v171, s[30:31]
	v_mfma_f32_16x16x32_f16 v[116:119], v[132:135], v[250:253], v[116:119]
	v_mfma_f32_16x16x32_f16 v[120:123], v[136:139], v[250:253], v[120:123]
	v_mfma_f32_16x16x32_f16 v[124:127], v[140:143], v[250:253], v[124:127]
	v_mfma_f32_16x16x32_f16 v[128:131], v[144:147], v[250:253], v[128:131]
	s_waitcnt lgkmcnt(0)
	s_mov_b32 s37, s52
	s_add_u32 s28, s28, 64
	s_addc_u32 s29, s29, 0
	s_add_u32 s30, s30, 64
	s_addc_u32 s31, s31, 0
	v_add_u32_e32 v169, s37, v164
	v_mfma_f32_16x16x32_f16 v[4:7], v[148:151], v[184:187], v[4:7]
	ds_read_b128 v[238:241], v169 offset:4112
	v_mfma_f32_16x16x32_f16 v[8:11], v[152:155], v[184:187], v[8:11]
	ds_read_b128 v[242:245], v169 offset:5136
	v_mfma_f32_16x16x32_f16 v[12:15], v[156:159], v[184:187], v[12:15]
	ds_read_b128 v[246:249], v169 offset:6160
	v_mfma_f32_16x16x32_f16 v[16:19], v[160:163], v[184:187], v[16:19]
	ds_read_b128 v[250:253], v169 offset:7184
	v_mfma_f32_16x16x32_f16 v[20:23], v[148:151], v[188:191], v[20:23]
	v_mfma_f32_16x16x32_f16 v[24:27], v[152:155], v[188:191], v[24:27]
	v_mfma_f32_16x16x32_f16 v[28:31], v[156:159], v[188:191], v[28:31]
	v_mfma_f32_16x16x32_f16 v[32:35], v[160:163], v[188:191], v[32:35]
	v_mfma_f32_16x16x32_f16 v[36:39], v[148:151], v[192:195], v[36:39]
	v_mfma_f32_16x16x32_f16 v[40:43], v[152:155], v[192:195], v[40:43]
	v_mfma_f32_16x16x32_f16 v[44:47], v[156:159], v[192:195], v[44:47]
	v_mfma_f32_16x16x32_f16 v[48:51], v[160:163], v[192:195], v[48:51]
	v_mfma_f32_16x16x32_f16 v[52:55], v[148:151], v[196:199], v[52:55]
	v_mfma_f32_16x16x32_f16 v[56:59], v[152:155], v[196:199], v[56:59]
	v_mfma_f32_16x16x32_f16 v[60:63], v[156:159], v[196:199], v[60:63]
	v_mfma_f32_16x16x32_f16 v[64:67], v[160:163], v[196:199], v[64:67]
	s_waitcnt vmcnt(8) lgkmcnt(0)
	s_barrier
	s_add_i32 s52, s37, 0x8000
	s_cmp_lg_u32 s37, 0x18000
	s_cselect_b32 s52, s52, 0
	v_add_u32_e32 v168, s52, v165
	v_add_u32_e32 v169, s52, v164
	s_add_u32 vcc_lo, s32, s37
	v_mfma_f32_16x16x32_f16 v[68:71], v[148:151], v[238:241], v[68:71]
	ds_read_b128 v[132:135], v168 offset:16
	ds_read_b128 v[184:187], v169 offset:16
	v_mfma_f32_16x16x32_f16 v[72:75], v[152:155], v[238:241], v[72:75]
	ds_read_b128 v[136:139], v168 offset:1040
	ds_read_b128 v[188:191], v169 offset:1040
	v_mfma_f32_16x16x32_f16 v[76:79], v[156:159], v[238:241], v[76:79]
	ds_read_b128 v[140:143], v168 offset:2064
	ds_read_b128 v[192:195], v169 offset:2064
	v_mfma_f32_16x16x32_f16 v[80:83], v[160:163], v[238:241], v[80:83]
	ds_read_b128 v[144:147], v168 offset:3088
	ds_read_b128 v[196:199], v169 offset:3088
	v_mfma_f32_16x16x32_f16 v[84:87], v[148:151], v[242:245], v[84:87]
	v_mfma_f32_16x16x32_f16 v[88:91], v[152:155], v[242:245], v[88:91]
	v_mfma_f32_16x16x32_f16 v[92:95], v[156:159], v[242:245], v[92:95]
	v_mfma_f32_16x16x32_f16 v[96:99], v[160:163], v[242:245], v[96:99]
	v_mfma_f32_16x16x32_f16 v[100:103], v[148:151], v[246:249], v[100:103]
	s_mov_b32 m0, vcc_lo
	s_nop 0
	global_load_lds_dwordx4 v170, s[28:29]
	v_mfma_f32_16x16x32_f16 v[104:107], v[152:155], v[246:249], v[104:107]
	s_add_u32 m0, vcc_lo, 0x400
	s_nop 0
	global_load_lds_dwordx4 v171, s[28:29]
	v_mfma_f32_16x16x32_f16 v[108:111], v[156:159], v[246:249], v[108:111]
	s_add_u32 m0, vcc_lo, 0x4000
	s_nop 0
	global_load_lds_dwordx4 v170, s[30:31]
	v_mfma_f32_16x16x32_f16 v[112:115], v[160:163], v[246:249], v[112:115]
	s_add_u32 m0, vcc_lo, 0x4400
	s_nop 0
	global_load_lds_dwordx4 v171, s[30:31]
	v_mfma_f32_16x16x32_f16 v[116:119], v[148:151], v[250:253], v[116:119]
	v_mfma_f32_16x16x32_f16 v[120:123], v[152:155], v[250:253], v[120:123]
	v_mfma_f32_16x16x32_f16 v[124:127], v[156:159], v[250:253], v[124:127]
	v_mfma_f32_16x16x32_f16 v[128:131], v[160:163], v[250:253], v[128:131]
	s_waitcnt lgkmcnt(0)
	s_mov_b32 s37, s52
	s_add_u32 s28, s28, 64
	s_addc_u32 s29, s29, 0
	s_add_u32 s30, s30, 64
	s_addc_u32 s31, s31, 0
	s_add_i32 s53, s53, 2
	s_cmp_lt_u32 s53, 28
	s_cbranch_scc1 .Lt_out1
	v_add_u32_e32 v169, s37, v164
	v_mfma_f32_16x16x32_f16 v[4:7], v[132:135], v[184:187], v[4:7]
	ds_read_b128 v[238:241], v169 offset:4112
	v_mfma_f32_16x16x32_f16 v[8:11], v[136:139], v[184:187], v[8:11]
	ds_read_b128 v[242:245], v169 offset:5136
	v_mfma_f32_16x16x32_f16 v[12:15], v[140:143], v[184:187], v[12:15]
	ds_read_b128 v[246:249], v169 offset:6160
	v_mfma_f32_16x16x32_f16 v[16:19], v[144:147], v[184:187], v[16:19]
	ds_read_b128 v[250:253], v169 offset:7184
	v_mfma_f32_16x16x32_f16 v[20:23], v[132:135], v[188:191], v[20:23]
	v_mfma_f32_16x16x32_f16 v[24:27], v[136:139], v[188:191], v[24:27]
	v_mfma_f32_16x16x32_f16 v[28:31], v[140:143], v[188:191], v[28:31]
	v_mfma_f32_16x16x32_f16 v[32:35], v[144:147], v[188:191], v[32:35]
	v_mfma_f32_16x16x32_f16 v[36:39], v[132:135], v[192:195], v[36:39]
	v_mfma_f32_16x16x32_f16 v[40:43], v[136:139], v[192:195], v[40:43]
	v_mfma_f32_16x16x32_f16 v[44:47], v[140:143], v[192:195], v[44:47]
	v_mfma_f32_16x16x32_f16 v[48:51], v[144:147], v[192:195], v[48:51]
	v_mfma_f32_16x16x32_f16 v[52:55], v[132:135], v[196:199], v[52:55]
	v_mfma_f32_16x16x32_f16 v[56:59], v[136:139], v[196:199], v[56:59]
	v_mfma_f32_16x16x32_f16 v[60:63], v[140:143], v[196:199], v[60:63]
	v_mfma_f32_16x16x32_f16 v[64:67], v[144:147], v[196:199], v[64:67]
	s_waitcnt vmcnt(8) lgkmcnt(0)
	s_barrier
	s_add_i32 s52, s37, 0x8000
	s_cmp_lg_u32 s37, 0x18000
	s_cselect_b32 s52, s52, 0
	v_add_u32_e32 v168, s52, v165
	v_add_u32_e32 v169, s52, v164
	v_mfma_f32_16x16x32_f16 v[68:71], v[132:135], v[238:241], v[68:71]
	ds_read_b128 v[148:151], v168 offset:16
	ds_read_b128 v[184:187], v169 offset:16
	v_mfma_f32_16x16x32_f16 v[72:75], v[136:139], v[238:241], v[72:75]
	ds_read_b128 v[152:155], v168 offset:1040
	ds_read_b128 v[188:191], v169 offset:1040
	v_mfma_f32_16x16x32_f16 v[76:79], v[140:143], v[238:241], v[76:79]
	ds_read_b128 v[156:159], v168 offset:2064
	ds_read_b128 v[192:195], v169 offset:2064
	v_mfma_f32_16x16x32_f16 v[80:83], v[144:147], v[238:241], v[80:83]
	ds_read_b128 v[160:163], v168 offset:3088
	ds_read_b128 v[196:199], v169 offset:3088
	v_mfma_f32_16x16x32_f16 v[84:87], v[132:135], v[242:245], v[84:87]
	v_mfma_f32_16x16x32_f16 v[88:91], v[136:139], v[242:245], v[88:91]
	v_mfma_f32_16x16x32_f16 v[92:95], v[140:143], v[242:245], v[92:95]
	v_mfma_f32_16x16x32_f16 v[96:99], v[144:147], v[242:245], v[96:99]
	v_mfma_f32_16x16x32_f16 v[100:103], v[132:135], v[246:249], v[100:103]
	v_mfma_f32_16x16x32_f16 v[104:107], v[136:139], v[246:249], v[104:107]
	v_mfma_f32_16x16x32_f16 v[108:111], v[140:143], v[246:249], v[108:111]
	v_mfma_f32_16x16x32_f16 v[112:115], v[144:147], v[246:249], v[112:115]
	v_mfma_f32_16x16x32_f16 v[116:119], v[132:135], v[250:253], v[116:119]
	v_mfma_f32_16x16x32_f16 v[120:123], v[136:139], v[250:253], v[120:123]
	v_mfma_f32_16x16x32_f16 v[124:127], v[140:143], v[250:253], v[124:127]
	v_mfma_f32_16x16x32_f16 v[128:131], v[144:147], v[250:253], v[128:131]
	s_waitcnt lgkmcnt(0)
	s_mov_b32 s37, s52
	v_add_u32_e32 v169, s37, v164
	v_mfma_f32_16x16x32_f16 v[4:7], v[148:151], v[184:187], v[4:7]
	ds_read_b128 v[238:241], v169 offset:4112
	v_mfma_f32_16x16x32_f16 v[8:11], v[152:155], v[184:187], v[8:11]
	ds_read_b128 v[242:245], v169 offset:5136
	v_mfma_f32_16x16x32_f16 v[12:15], v[156:159], v[184:187], v[12:15]
	ds_read_b128 v[246:249], v169 offset:6160
	v_mfma_f32_16x16x32_f16 v[16:19], v[160:163], v[184:187], v[16:19]
	ds_read_b128 v[250:253], v169 offset:7184
	v_mfma_f32_16x16x32_f16 v[20:23], v[148:151], v[188:191], v[20:23]
	v_mfma_f32_16x16x32_f16 v[24:27], v[152:155], v[188:191], v[24:27]
	v_mfma_f32_16x16x32_f16 v[28:31], v[156:159], v[188:191], v[28:31]
	v_mfma_f32_16x16x32_f16 v[32:35], v[160:163], v[188:191], v[32:35]
	v_mfma_f32_16x16x32_f16 v[36:39], v[148:151], v[192:195], v[36:39]
	v_mfma_f32_16x16x32_f16 v[40:43], v[152:155], v[192:195], v[40:43]
	v_mfma_f32_16x16x32_f16 v[44:47], v[156:159], v[192:195], v[44:47]
	v_mfma_f32_16x16x32_f16 v[48:51], v[160:163], v[192:195], v[48:51]
	v_mfma_f32_16x16x32_f16 v[52:55], v[148:151], v[196:199], v[52:55]
	v_mfma_f32_16x16x32_f16 v[56:59], v[152:155], v[196:199], v[56:59]
	v_mfma_f32_16x16x32_f16 v[60:63], v[156:159], v[196:199], v[60:63]
	v_mfma_f32_16x16x32_f16 v[64:67], v[160:163], v[196:199], v[64:67]
	s_waitcnt vmcnt(4) lgkmcnt(0)
	s_barrier
	s_add_i32 s52, s37, 0x8000
	s_cmp_lg_u32 s37, 0x18000
	s_cselect_b32 s52, s52, 0
	v_add_u32_e32 v168, s52, v165
	v_add_u32_e32 v169, s52, v164
	v_mfma_f32_16x16x32_f16 v[68:71], v[148:151], v[238:241], v[68:71]
	ds_read_b128 v[132:135], v168 offset:16
	ds_read_b128 v[184:187], v169 offset:16
	v_mfma_f32_16x16x32_f16 v[72:75], v[152:155], v[238:241], v[72:75]
	ds_read_b128 v[136:139], v168 offset:1040
	ds_read_b128 v[188:191], v169 offset:1040
	v_mfma_f32_16x16x32_f16 v[76:79], v[156:159], v[238:241], v[76:79]
	ds_read_b128 v[140:143], v168 offset:2064
	ds_read_b128 v[192:195], v169 offset:2064
	v_mfma_f32_16x16x32_f16 v[80:83], v[160:163], v[238:241], v[80:83]
	ds_read_b128 v[144:147], v168 offset:3088
	ds_read_b128 v[196:199], v169 offset:3088
	v_mfma_f32_16x16x32_f16 v[84:87], v[148:151], v[242:245], v[84:87]
	v_mfma_f32_16x16x32_f16 v[88:91], v[152:155], v[242:245], v[88:91]
	v_mfma_f32_16x16x32_f16 v[92:95], v[156:159], v[242:245], v[92:95]
	v_mfma_f32_16x16x32_f16 v[96:99], v[160:163], v[242:245], v[96:99]
	v_mfma_f32_16x16x32_f16 v[100:103], v[148:151], v[246:249], v[100:103]
	v_mfma_f32_16x16x32_f16 v[104:107], v[152:155], v[246:249], v[104:107]
	v_mfma_f32_16x16x32_f16 v[108:111], v[156:159], v[246:249], v[108:111]
	v_mfma_f32_16x16x32_f16 v[112:115], v[160:163], v[246:249], v[112:115]
	v_mfma_f32_16x16x32_f16 v[116:119], v[148:151], v[250:253], v[116:119]
	v_mfma_f32_16x16x32_f16 v[120:123], v[152:155], v[250:253], v[120:123]
	v_mfma_f32_16x16x32_f16 v[124:127], v[156:159], v[250:253], v[124:127]
	v_mfma_f32_16x16x32_f16 v[128:131], v[160:163], v[250:253], v[128:131]
	s_waitcnt lgkmcnt(0)
	s_mov_b32 s37, s52
	v_add_u32_e32 v169, s37, v164
	v_mfma_f32_16x16x32_f16 v[4:7], v[132:135], v[184:187], v[4:7]
	ds_read_b128 v[238:241], v169 offset:4112
	v_mfma_f32_16x16x32_f16 v[8:11], v[136:139], v[184:187], v[8:11]
	ds_read_b128 v[242:245], v169 offset:5136
	v_mfma_f32_16x16x32_f16 v[12:15], v[140:143], v[184:187], v[12:15]
	ds_read_b128 v[246:249], v169 offset:6160
	v_mfma_f32_16x16x32_f16 v[16:19], v[144:147], v[184:187], v[16:19]
	ds_read_b128 v[250:253], v169 offset:7184
	v_mfma_f32_16x16x32_f16 v[20:23], v[132:135], v[188:191], v[20:23]
	v_mfma_f32_16x16x32_f16 v[24:27], v[136:139], v[188:191], v[24:27]
	v_mfma_f32_16x16x32_f16 v[28:31], v[140:143], v[188:191], v[28:31]
	v_mfma_f32_16x16x32_f16 v[32:35], v[144:147], v[188:191], v[32:35]
	v_mfma_f32_16x16x32_f16 v[36:39], v[132:135], v[192:195], v[36:39]
	v_mfma_f32_16x16x32_f16 v[40:43], v[136:139], v[192:195], v[40:43]
	v_mfma_f32_16x16x32_f16 v[44:47], v[140:143], v[192:195], v[44:47]
	v_mfma_f32_16x16x32_f16 v[48:51], v[144:147], v[192:195], v[48:51]
	v_mfma_f32_16x16x32_f16 v[52:55], v[132:135], v[196:199], v[52:55]
	v_mfma_f32_16x16x32_f16 v[56:59], v[136:139], v[196:199], v[56:59]
	v_mfma_f32_16x16x32_f16 v[60:63], v[140:143], v[196:199], v[60:63]
	v_mfma_f32_16x16x32_f16 v[64:67], v[144:147], v[196:199], v[64:67]
	s_waitcnt vmcnt(0) lgkmcnt(0)
	s_barrier
	s_add_i32 s52, s37, 0x8000
	s_cmp_lg_u32 s37, 0x18000
	s_cselect_b32 s52, s52, 0
	v_add_u32_e32 v168, s52, v165
	v_add_u32_e32 v169, s52, v164
	v_mfma_f32_16x16x32_f16 v[68:71], v[132:135], v[238:241], v[68:71]
	ds_read_b128 v[148:151], v168 offset:16
	ds_read_b128 v[184:187], v169 offset:16
	v_mfma_f32_16x16x32_f16 v[72:75], v[136:139], v[238:241], v[72:75]
	ds_read_b128 v[152:155], v168 offset:1040
	ds_read_b128 v[188:191], v169 offset:1040
	v_mfma_f32_16x16x32_f16 v[76:79], v[140:143], v[238:241], v[76:79]
	ds_read_b128 v[156:159], v168 offset:2064
	ds_read_b128 v[192:195], v169 offset:2064
	v_mfma_f32_16x16x32_f16 v[80:83], v[144:147], v[238:241], v[80:83]
	ds_read_b128 v[160:163], v168 offset:3088
	ds_read_b128 v[196:199], v169 offset:3088
	v_mfma_f32_16x16x32_f16 v[84:87], v[132:135], v[242:245], v[84:87]
	v_mfma_f32_16x16x32_f16 v[88:91], v[136:139], v[242:245], v[88:91]
	v_mfma_f32_16x16x32_f16 v[92:95], v[140:143], v[242:245], v[92:95]
	v_mfma_f32_16x16x32_f16 v[96:99], v[144:147], v[242:245], v[96:99]
	v_mfma_f32_16x16x32_f16 v[100:103], v[132:135], v[246:249], v[100:103]
	v_mfma_f32_16x16x32_f16 v[104:107], v[136:139], v[246:249], v[104:107]
	v_mfma_f32_16x16x32_f16 v[108:111], v[140:143], v[246:249], v[108:111]
	v_mfma_f32_16x16x32_f16 v[112:115], v[144:147], v[246:249], v[112:115]
	v_mfma_f32_16x16x32_f16 v[116:119], v[132:135], v[250:253], v[116:119]
	v_mfma_f32_16x16x32_f16 v[120:123], v[136:139], v[250:253], v[120:123]
	v_mfma_f32_16x16x32_f16 v[124:127], v[140:143], v[250:253], v[124:127]
	v_mfma_f32_16x16x32_f16 v[128:131], v[144:147], v[250:253], v[128:131]
	s_waitcnt lgkmcnt(0)
	s_mov_b32 s37, s52
	v_add_u32_e32 v169, s37, v164
	v_mfma_f32_16x16x32_f16 v[4:7], v[148:151], v[184:187], v[4:7]
	ds_read_b128 v[238:241], v169 offset:4112
	v_mfma_f32_16x16x32_f16 v[8:11], v[152:155], v[184:187], v[8:11]
	ds_read_b128 v[242:245], v169 offset:5136
	v_mfma_f32_16x16x32_f16 v[12:15], v[156:159], v[184:187], v[12:15]
	ds_read_b128 v[246:249], v169 offset:6160
	v_mfma_f32_16x16x32_f16 v[16:19], v[160:163], v[184:187], v[16:19]
	ds_read_b128 v[250:253], v169 offset:7184
	v_mfma_f32_16x16x32_f16 v[20:23], v[148:151], v[188:191], v[20:23]
	v_mfma_f32_16x16x32_f16 v[24:27], v[152:155], v[188:191], v[24:27]
	v_mfma_f32_16x16x32_f16 v[28:31], v[156:159], v[188:191], v[28:31]
	v_mfma_f32_16x16x32_f16 v[32:35], v[160:163], v[188:191], v[32:35]
	v_mfma_f32_16x16x32_f16 v[36:39], v[148:151], v[192:195], v[36:39]
	v_mfma_f32_16x16x32_f16 v[40:43], v[152:155], v[192:195], v[40:43]
	v_mfma_f32_16x16x32_f16 v[44:47], v[156:159], v[192:195], v[44:47]
	v_mfma_f32_16x16x32_f16 v[48:51], v[160:163], v[192:195], v[48:51]
	v_mfma_f32_16x16x32_f16 v[52:55], v[148:151], v[196:199], v[52:55]
	v_mfma_f32_16x16x32_f16 v[56:59], v[152:155], v[196:199], v[56:59]
	v_mfma_f32_16x16x32_f16 v[60:63], v[156:159], v[196:199], v[60:63]
	v_mfma_f32_16x16x32_f16 v[64:67], v[160:163], v[196:199], v[64:67]
	s_waitcnt lgkmcnt(0)
	s_barrier
	v_mfma_f32_16x16x32_f16 v[68:71], v[148:151], v[238:241], v[68:71]
	v_mfma_f32_16x16x32_f16 v[72:75], v[152:155], v[238:241], v[72:75]
	v_mfma_f32_16x16x32_f16 v[76:79], v[156:159], v[238:241], v[76:79]
	v_mfma_f32_16x16x32_f16 v[80:83], v[160:163], v[238:241], v[80:83]
	v_mfma_f32_16x16x32_f16 v[84:87], v[148:151], v[242:245], v[84:87]
	v_mfma_f32_16x16x32_f16 v[88:91], v[152:155], v[242:245], v[88:91]
	v_mfma_f32_16x16x32_f16 v[92:95], v[156:159], v[242:245], v[92:95]
	v_mfma_f32_16x16x32_f16 v[96:99], v[160:163], v[242:245], v[96:99]
	v_mfma_f32_16x16x32_f16 v[100:103], v[148:151], v[246:249], v[100:103]
	v_mfma_f32_16x16x32_f16 v[104:107], v[152:155], v[246:249], v[104:107]
	v_mfma_f32_16x16x32_f16 v[108:111], v[156:159], v[246:249], v[108:111]
	v_mfma_f32_16x16x32_f16 v[112:115], v[160:163], v[246:249], v[112:115]
	v_mfma_f32_16x16x32_f16 v[116:119], v[148:151], v[250:253], v[116:119]
	v_mfma_f32_16x16x32_f16 v[120:123], v[152:155], v[250:253], v[120:123]
	v_mfma_f32_16x16x32_f16 v[124:127], v[156:159], v[250:253], v[124:127]
	v_mfma_f32_16x16x32_f16 v[128:131], v[160:163], v[250:253], v[128:131]
	s_sub_u32 s77, s36, 0x1000
	s_lshr_b32 s77, s77, 12
	s_add_u32 s77, s77, 1
	s_cmp_lt_u32 s36, 0x1000
	s_cselect_b32 s77, 0, s77
	s_mul_i32 s77, s77, 0x6000
	s_add_u32 s68, s26, s77
	s_addc_u32 s69, s27, 0
	s_add_u32 s68, s68, 0x20000
	s_addc_u32 s69, s69, 0
	s_lshl_b32 s82, s36, 11
	s_add_u32 s80, s46, s82
	s_addc_u32 s81, s47, 0
	s_lshl_b32 s82, s35, 1
	s_add_u32 s80, s80, s82
	s_addc_u32 s81, s81, 0
	v_and_b32_e32 v172, 15, v200
	v_bfe_u32 v173, v200, 4, 2
	v_bfe_u32 v174, v200, 6, 2
	v_bfe_u32 v175, v200, 8, 1
	v_lshlrev_b32_e32 v176, 6, v174
	v_lshl_or_b32 v176, v173, 2, v176
	v_lshl_or_b32 v175, v175, 7, v172
	v_lshlrev_b32_e32 v175, 11, v175
	v_lshl_add_u32 v177, v176, 1, v175
	v_add_u32_e32 v176, s35, v176
	v_lshlrev_b32_e32 v176, 2, v176
	global_load_dwordx4 v[132:135], v176, s[68:69]
	global_load_dwordx4 v[136:139], v176, s[68:69] offset:64
	global_load_dwordx4 v[140:143], v176, s[68:69] offset:128
	global_load_dwordx4 v[144:147], v176, s[68:69] offset:192
	v_and_b32_e32 v172, 1, v173
	v_mul_u32_u24_e32 v172, 24, v172
	v_add_u32_e32 v177, v177, v172
	v_mov_b32_e32 v178, v177
	global_load_dwordx4 v[184:187], v178, s[80:81]
	global_load_dwordx4 v[188:191], v178, s[80:81] offset:64
	v_add_u32_e32 v178, 0x8000, v178
	global_load_dwordx4 v[238:241], v178, s[80:81]
	global_load_dwordx4 v[242:245], v178, s[80:81] offset:64
	s_waitcnt vmcnt(3)
	v_permlane16_swap_b32_e32 v184, v186
	v_permlane16_swap_b32_e32 v185, v187
	v_cvt_f32_f16_e32 v164, v184
	v_cvt_f32_f16_sdwa v165, v184 dst_sel:DWORD dst_unused:UNUSED_PAD src0_sel:WORD_1
	v_cvt_f32_f16_e32 v166, v185
	v_cvt_f32_f16_sdwa v167, v185 dst_sel:DWORD dst_unused:UNUSED_PAD src0_sel:WORD_1
	v_pk_mul_f32 v[164:165], v[164:165], s[84:85] op_sel_hi:[1,0]
	v_pk_mul_f32 v[166:167], v[166:167], s[84:85] op_sel_hi:[1,0]
	v_pk_fma_f32 v[4:5], v[4:5], v[132:133], v[164:165]
	v_pk_fma_f32 v[6:7], v[6:7], v[134:135], v[166:167]
	v_cvt_pk_f16_f32 v172, v4, v5
	v_cvt_pk_f16_f32 v173, v6, v7
	v_cvt_f32_f16_e32 v164, v186
	v_cvt_f32_f16_sdwa v165, v186 dst_sel:DWORD dst_unused:UNUSED_PAD src0_sel:WORD_1
	v_cvt_f32_f16_e32 v166, v187
	v_cvt_f32_f16_sdwa v167, v187 dst_sel:DWORD dst_unused:UNUSED_PAD src0_sel:WORD_1
	v_pk_mul_f32 v[164:165], v[164:165], s[84:85] op_sel_hi:[1,0]
	v_pk_mul_f32 v[166:167], v[166:167], s[84:85] op_sel_hi:[1,0]
	v_pk_fma_f32 v[8:9], v[8:9], v[136:137], v[164:165]
	v_pk_fma_f32 v[10:11], v[10:11], v[138:139], v[166:167]
	v_cvt_pk_f16_f32 v174, v8, v9
	v_cvt_pk_f16_f32 v175, v10, v11
	s_nop 1
	v_permlane16_swap_b32_e32 v172, v174
	v_permlane16_swap_b32_e32 v173, v175
	global_store_dwordx4 v177, v[172:175], s[80:81]
	s_waitcnt vmcnt(3)
	v_permlane16_swap_b32_e32 v188, v190
	v_permlane16_swap_b32_e32 v189, v191
	v_cvt_f32_f16_e32 v164, v188
	v_cvt_f32_f16_sdwa v165, v188 dst_sel:DWORD dst_unused:UNUSED_PAD src0_sel:WORD_1
	v_cvt_f32_f16_e32 v166, v189
	v_cvt_f32_f16_sdwa v167, v189 dst_sel:DWORD dst_unused:UNUSED_PAD src0_sel:WORD_1
	v_pk_mul_f32 v[164:165], v[164:165], s[84:85] op_sel_hi:[1,0]
	v_pk_mul_f32 v[166:167], v[166:167], s[84:85] op_sel_hi:[1,0]
	v_pk_fma_f32 v[12:13], v[12:13], v[140:141], v[164:165]
	v_pk_fma_f32 v[14:15], v[14:15], v[142:143], v[166:167]
	v_cvt_pk_f16_f32 v228, v12, v13
	v_cvt_pk_f16_f32 v229, v14, v15
	v_cvt_f32_f16_e32 v164, v190
	v_cvt_f32_f16_sdwa v165, v190 dst_sel:DWORD dst_unused:UNUSED_PAD src0_sel:WORD_1
	v_cvt_f32_f16_e32 v166, v191
	v_cvt_f32_f16_sdwa v167, v191 dst_sel:DWORD dst_unused:UNUSED_PAD src0_sel:WORD_1
	v_pk_mul_f32 v[164:165], v[164:165], s[84:85] op_sel_hi:[1,0]
	v_pk_mul_f32 v[166:167], v[166:167], s[84:85] op_sel_hi:[1,0]
	v_pk_fma_f32 v[16:17], v[16:17], v[144:145], v[164:165]
	v_pk_fma_f32 v[18:19], v[18:19], v[146:147], v[166:167]
	v_cvt_pk_f16_f32 v230, v16, v17
	v_cvt_pk_f16_f32 v231, v18, v19
	s_nop 1
	v_permlane16_swap_b32_e32 v228, v230
	v_permlane16_swap_b32_e32 v229, v231
	global_store_dwordx4 v177, v[228:231], s[80:81] offset:64
	v_add_u32_e32 v177, 0x8000, v177
	v_add_u32_e32 v178, 0x8000, v178
	global_load_dwordx4 v[184:187], v178, s[80:81]
	global_load_dwordx4 v[188:191], v178, s[80:81] offset:64
	s_waitcnt vmcnt(5)
	v_permlane16_swap_b32_e32 v238, v240
	v_permlane16_swap_b32_e32 v239, v241
	v_cvt_f32_f16_e32 v164, v238
	v_cvt_f32_f16_sdwa v165, v238 dst_sel:DWORD dst_unused:UNUSED_PAD src0_sel:WORD_1
	v_cvt_f32_f16_e32 v166, v239
	v_cvt_f32_f16_sdwa v167, v239 dst_sel:DWORD dst_unused:UNUSED_PAD src0_sel:WORD_1
	v_pk_mul_f32 v[164:165], v[164:165], s[84:85] op_sel_hi:[1,0]
	v_pk_mul_f32 v[166:167], v[166:167], s[84:85] op_sel_hi:[1,0]
	v_pk_fma_f32 v[20:21], v[20:21], v[132:133], v[164:165]
	v_pk_fma_f32 v[22:23], v[22:23], v[134:135], v[166:167]
	v_cvt_pk_f16_f32 v172, v20, v21
	v_cvt_pk_f16_f32 v173, v22, v23
	v_cvt_f32_f16_e32 v164, v240
	v_cvt_f32_f16_sdwa v165, v240 dst_sel:DWORD dst_unused:UNUSED_PAD src0_sel:WORD_1
	v_cvt_f32_f16_e32 v166, v241
	v_cvt_f32_f16_sdwa v167, v241 dst_sel:DWORD dst_unused:UNUSED_PAD src0_sel:WORD_1
	v_pk_mul_f32 v[164:165], v[164:165], s[84:85] op_sel_hi:[1,0]
	v_pk_mul_f32 v[166:167], v[166:167], s[84:85] op_sel_hi:[1,0]
	v_pk_fma_f32 v[24:25], v[24:25], v[136:137], v[164:165]
	v_pk_fma_f32 v[26:27], v[26:27], v[138:139], v[166:167]
	v_cvt_pk_f16_f32 v174, v24, v25
	v_cvt_pk_f16_f32 v175, v26, v27
	s_nop 1
	v_permlane16_swap_b32_e32 v172, v174
	v_permlane16_swap_b32_e32 v173, v175
	global_store_dwordx4 v177, v[172:175], s[80:81]
	s_waitcnt vmcnt(5)
	v_permlane16_swap_b32_e32 v242, v244
	v_permlane16_swap_b32_e32 v243, v245
	v_cvt_f32_f16_e32 v164, v242
	v_cvt_f32_f16_sdwa v165, v242 dst_sel:DWORD dst_unused:UNUSED_PAD src0_sel:WORD_1
	v_cvt_f32_f16_e32 v166, v243
	v_cvt_f32_f16_sdwa v167, v243 dst_sel:DWORD dst_unused:UNUSED_PAD src0_sel:WORD_1
	v_pk_mul_f32 v[164:165], v[164:165], s[84:85] op_sel_hi:[1,0]
	v_pk_mul_f32 v[166:167], v[166:167], s[84:85] op_sel_hi:[1,0]
	v_pk_fma_f32 v[28:29], v[28:29], v[140:141], v[164:165]
	v_pk_fma_f32 v[30:31], v[30:31], v[142:143], v[166:167]
	v_cvt_pk_f16_f32 v228, v28, v29
	v_cvt_pk_f16_f32 v229, v30, v31
	v_cvt_f32_f16_e32 v164, v244
	v_cvt_f32_f16_sdwa v165, v244 dst_sel:DWORD dst_unused:UNUSED_PAD src0_sel:WORD_1
	v_cvt_f32_f16_e32 v166, v245
	v_cvt_f32_f16_sdwa v167, v245 dst_sel:DWORD dst_unused:UNUSED_PAD src0_sel:WORD_1
	v_pk_mul_f32 v[164:165], v[164:165], s[84:85] op_sel_hi:[1,0]
	v_pk_mul_f32 v[166:167], v[166:167], s[84:85] op_sel_hi:[1,0]
	v_pk_fma_f32 v[32:33], v[32:33], v[144:145], v[164:165]
	v_pk_fma_f32 v[34:35], v[34:35], v[146:147], v[166:167]
	v_cvt_pk_f16_f32 v230, v32, v33
	v_cvt_pk_f16_f32 v231, v34, v35
	s_nop 1
	v_permlane16_swap_b32_e32 v228, v230
	v_permlane16_swap_b32_e32 v229, v231
	global_store_dwordx4 v177, v[228:231], s[80:81] offset:64
	v_add_u32_e32 v177, 0x8000, v177
	v_add_u32_e32 v178, 0x8000, v178
	global_load_dwordx4 v[238:241], v178, s[80:81]
	global_load_dwordx4 v[242:245], v178, s[80:81] offset:64
	s_waitcnt vmcnt(5)
	v_permlane16_swap_b32_e32 v184, v186
	v_permlane16_swap_b32_e32 v185, v187
	v_cvt_f32_f16_e32 v164, v184
	v_cvt_f32_f16_sdwa v165, v184 dst_sel:DWORD dst_unused:UNUSED_PAD src0_sel:WORD_1
	v_cvt_f32_f16_e32 v166, v185
	v_cvt_f32_f16_sdwa v167, v185 dst_sel:DWORD dst_unused:UNUSED_PAD src0_sel:WORD_1
	v_pk_mul_f32 v[164:165], v[164:165], s[84:85] op_sel_hi:[1,0]
	v_pk_mul_f32 v[166:167], v[166:167], s[84:85] op_sel_hi:[1,0]
	v_pk_fma_f32 v[36:37], v[36:37], v[132:133], v[164:165]
	v_pk_fma_f32 v[38:39], v[38:39], v[134:135], v[166:167]
	v_cvt_pk_f16_f32 v172, v36, v37
	v_cvt_pk_f16_f32 v173, v38, v39
	v_cvt_f32_f16_e32 v164, v186
	v_cvt_f32_f16_sdwa v165, v186 dst_sel:DWORD dst_unused:UNUSED_PAD src0_sel:WORD_1
	v_cvt_f32_f16_e32 v166, v187
	v_cvt_f32_f16_sdwa v167, v187 dst_sel:DWORD dst_unused:UNUSED_PAD src0_sel:WORD_1
	v_pk_mul_f32 v[164:165], v[164:165], s[84:85] op_sel_hi:[1,0]
	v_pk_mul_f32 v[166:167], v[166:167], s[84:85] op_sel_hi:[1,0]
	v_pk_fma_f32 v[40:41], v[40:41], v[136:137], v[164:165]
	v_pk_fma_f32 v[42:43], v[42:43], v[138:139], v[166:167]
	v_cvt_pk_f16_f32 v174, v40, v41
	v_cvt_pk_f16_f32 v175, v42, v43
	s_nop 1
	v_permlane16_swap_b32_e32 v172, v174
	v_permlane16_swap_b32_e32 v173, v175
	global_store_dwordx4 v177, v[172:175], s[80:81]
	s_waitcnt vmcnt(5)
	v_permlane16_swap_b32_e32 v188, v190
	v_permlane16_swap_b32_e32 v189, v191
	v_cvt_f32_f16_e32 v164, v188
	v_cvt_f32_f16_sdwa v165, v188 dst_sel:DWORD dst_unused:UNUSED_PAD src0_sel:WORD_1
	v_cvt_f32_f16_e32 v166, v189
	v_cvt_f32_f16_sdwa v167, v189 dst_sel:DWORD dst_unused:UNUSED_PAD src0_sel:WORD_1
	v_pk_mul_f32 v[164:165], v[164:165], s[84:85] op_sel_hi:[1,0]
	v_pk_mul_f32 v[166:167], v[166:167], s[84:85] op_sel_hi:[1,0]
	v_pk_fma_f32 v[44:45], v[44:45], v[140:141], v[164:165]
	v_pk_fma_f32 v[46:47], v[46:47], v[142:143], v[166:167]
	v_cvt_pk_f16_f32 v228, v44, v45
	v_cvt_pk_f16_f32 v229, v46, v47
	v_cvt_f32_f16_e32 v164, v190
	v_cvt_f32_f16_sdwa v165, v190 dst_sel:DWORD dst_unused:UNUSED_PAD src0_sel:WORD_1
	v_cvt_f32_f16_e32 v166, v191
	v_cvt_f32_f16_sdwa v167, v191 dst_sel:DWORD dst_unused:UNUSED_PAD src0_sel:WORD_1
	v_pk_mul_f32 v[164:165], v[164:165], s[84:85] op_sel_hi:[1,0]
	v_pk_mul_f32 v[166:167], v[166:167], s[84:85] op_sel_hi:[1,0]
	v_pk_fma_f32 v[48:49], v[48:49], v[144:145], v[164:165]
	v_pk_fma_f32 v[50:51], v[50:51], v[146:147], v[166:167]
	v_cvt_pk_f16_f32 v230, v48, v49
	v_cvt_pk_f16_f32 v231, v50, v51
	s_nop 1
	v_permlane16_swap_b32_e32 v228, v230
	v_permlane16_swap_b32_e32 v229, v231
	global_store_dwordx4 v177, v[228:231], s[80:81] offset:64
	v_add_u32_e32 v177, 0x8000, v177
	v_add_u32_e32 v178, 0x8000, v178
	global_load_dwordx4 v[184:187], v178, s[80:81]
	global_load_dwordx4 v[188:191], v178, s[80:81] offset:64
	s_waitcnt vmcnt(5)
	v_permlane16_swap_b32_e32 v238, v240
	v_permlane16_swap_b32_e32 v239, v241
	v_cvt_f32_f16_e32 v164, v238
	v_cvt_f32_f16_sdwa v165, v238 dst_sel:DWORD dst_unused:UNUSED_PAD src0_sel:WORD_1
	v_cvt_f32_f16_e32 v166, v239
	v_cvt_f32_f16_sdwa v167, v239 dst_sel:DWORD dst_unused:UNUSED_PAD src0_sel:WORD_1
	v_pk_mul_f32 v[164:165], v[164:165], s[84:85] op_sel_hi:[1,0]
	v_pk_mul_f32 v[166:167], v[166:167], s[84:85] op_sel_hi:[1,0]
	v_pk_fma_f32 v[52:53], v[52:53], v[132:133], v[164:165]
	v_pk_fma_f32 v[54:55], v[54:55], v[134:135], v[166:167]
	v_cvt_pk_f16_f32 v172, v52, v53
	v_cvt_pk_f16_f32 v173, v54, v55
	v_cvt_f32_f16_e32 v164, v240
	v_cvt_f32_f16_sdwa v165, v240 dst_sel:DWORD dst_unused:UNUSED_PAD src0_sel:WORD_1
	v_cvt_f32_f16_e32 v166, v241
	v_cvt_f32_f16_sdwa v167, v241 dst_sel:DWORD dst_unused:UNUSED_PAD src0_sel:WORD_1
	v_pk_mul_f32 v[164:165], v[164:165], s[84:85] op_sel_hi:[1,0]
	v_pk_mul_f32 v[166:167], v[166:167], s[84:85] op_sel_hi:[1,0]
	v_pk_fma_f32 v[56:57], v[56:57], v[136:137], v[164:165]
	v_pk_fma_f32 v[58:59], v[58:59], v[138:139], v[166:167]
	v_cvt_pk_f16_f32 v174, v56, v57
	v_cvt_pk_f16_f32 v175, v58, v59
	s_nop 1
	v_permlane16_swap_b32_e32 v172, v174
	v_permlane16_swap_b32_e32 v173, v175
	global_store_dwordx4 v177, v[172:175], s[80:81]
	s_waitcnt vmcnt(5)
	v_permlane16_swap_b32_e32 v242, v244
	v_permlane16_swap_b32_e32 v243, v245
	v_cvt_f32_f16_e32 v164, v242
	v_cvt_f32_f16_sdwa v165, v242 dst_sel:DWORD dst_unused:UNUSED_PAD src0_sel:WORD_1
	v_cvt_f32_f16_e32 v166, v243
	v_cvt_f32_f16_sdwa v167, v243 dst_sel:DWORD dst_unused:UNUSED_PAD src0_sel:WORD_1
	v_pk_mul_f32 v[164:165], v[164:165], s[84:85] op_sel_hi:[1,0]
	v_pk_mul_f32 v[166:167], v[166:167], s[84:85] op_sel_hi:[1,0]
	v_pk_fma_f32 v[60:61], v[60:61], v[140:141], v[164:165]
	v_pk_fma_f32 v[62:63], v[62:63], v[142:143], v[166:167]
	v_cvt_pk_f16_f32 v228, v60, v61
	v_cvt_pk_f16_f32 v229, v62, v63
	v_cvt_f32_f16_e32 v164, v244
	v_cvt_f32_f16_sdwa v165, v244 dst_sel:DWORD dst_unused:UNUSED_PAD src0_sel:WORD_1
	v_cvt_f32_f16_e32 v166, v245
	v_cvt_f32_f16_sdwa v167, v245 dst_sel:DWORD dst_unused:UNUSED_PAD src0_sel:WORD_1
	v_pk_mul_f32 v[164:165], v[164:165], s[84:85] op_sel_hi:[1,0]
	v_pk_mul_f32 v[166:167], v[166:167], s[84:85] op_sel_hi:[1,0]
	v_pk_fma_f32 v[64:65], v[64:65], v[144:145], v[164:165]
	v_pk_fma_f32 v[66:67], v[66:67], v[146:147], v[166:167]
	v_cvt_pk_f16_f32 v230, v64, v65
	v_cvt_pk_f16_f32 v231, v66, v67
	s_nop 1
	v_permlane16_swap_b32_e32 v228, v230
	v_permlane16_swap_b32_e32 v229, v231
	global_store_dwordx4 v177, v[228:231], s[80:81] offset:64
	v_add_u32_e32 v177, 0x8000, v177
	v_add_u32_e32 v178, 0x8000, v178
	global_load_dwordx4 v[238:241], v178, s[80:81]
	global_load_dwordx4 v[242:245], v178, s[80:81] offset:64
	s_waitcnt vmcnt(5)
	v_permlane16_swap_b32_e32 v184, v186
	v_permlane16_swap_b32_e32 v185, v187
	v_cvt_f32_f16_e32 v164, v184
	v_cvt_f32_f16_sdwa v165, v184 dst_sel:DWORD dst_unused:UNUSED_PAD src0_sel:WORD_1
	v_cvt_f32_f16_e32 v166, v185
	v_cvt_f32_f16_sdwa v167, v185 dst_sel:DWORD dst_unused:UNUSED_PAD src0_sel:WORD_1
	v_pk_mul_f32 v[164:165], v[164:165], s[84:85] op_sel_hi:[1,0]
	v_pk_mul_f32 v[166:167], v[166:167], s[84:85] op_sel_hi:[1,0]
	v_pk_fma_f32 v[68:69], v[68:69], v[132:133], v[164:165]
	v_pk_fma_f32 v[70:71], v[70:71], v[134:135], v[166:167]
	v_cvt_pk_f16_f32 v172, v68, v69
	v_cvt_pk_f16_f32 v173, v70, v71
	v_cvt_f32_f16_e32 v164, v186
	v_cvt_f32_f16_sdwa v165, v186 dst_sel:DWORD dst_unused:UNUSED_PAD src0_sel:WORD_1
	v_cvt_f32_f16_e32 v166, v187
	v_cvt_f32_f16_sdwa v167, v187 dst_sel:DWORD dst_unused:UNUSED_PAD src0_sel:WORD_1
	v_pk_mul_f32 v[164:165], v[164:165], s[84:85] op_sel_hi:[1,0]
	v_pk_mul_f32 v[166:167], v[166:167], s[84:85] op_sel_hi:[1,0]
	v_pk_fma_f32 v[72:73], v[72:73], v[136:137], v[164:165]
	v_pk_fma_f32 v[74:75], v[74:75], v[138:139], v[166:167]
	v_cvt_pk_f16_f32 v174, v72, v73
	v_cvt_pk_f16_f32 v175, v74, v75
	s_nop 1
	v_permlane16_swap_b32_e32 v172, v174
	v_permlane16_swap_b32_e32 v173, v175
	global_store_dwordx4 v177, v[172:175], s[80:81]
	s_waitcnt vmcnt(5)
	v_permlane16_swap_b32_e32 v188, v190
	v_permlane16_swap_b32_e32 v189, v191
	v_cvt_f32_f16_e32 v164, v188
	v_cvt_f32_f16_sdwa v165, v188 dst_sel:DWORD dst_unused:UNUSED_PAD src0_sel:WORD_1
	v_cvt_f32_f16_e32 v166, v189
	v_cvt_f32_f16_sdwa v167, v189 dst_sel:DWORD dst_unused:UNUSED_PAD src0_sel:WORD_1
	v_pk_mul_f32 v[164:165], v[164:165], s[84:85] op_sel_hi:[1,0]
	v_pk_mul_f32 v[166:167], v[166:167], s[84:85] op_sel_hi:[1,0]
	v_pk_fma_f32 v[76:77], v[76:77], v[140:141], v[164:165]
	v_pk_fma_f32 v[78:79], v[78:79], v[142:143], v[166:167]
	v_cvt_pk_f16_f32 v228, v76, v77
	v_cvt_pk_f16_f32 v229, v78, v79
	v_cvt_f32_f16_e32 v164, v190
	v_cvt_f32_f16_sdwa v165, v190 dst_sel:DWORD dst_unused:UNUSED_PAD src0_sel:WORD_1
	v_cvt_f32_f16_e32 v166, v191
	v_cvt_f32_f16_sdwa v167, v191 dst_sel:DWORD dst_unused:UNUSED_PAD src0_sel:WORD_1
	v_pk_mul_f32 v[164:165], v[164:165], s[84:85] op_sel_hi:[1,0]
	v_pk_mul_f32 v[166:167], v[166:167], s[84:85] op_sel_hi:[1,0]
	v_pk_fma_f32 v[80:81], v[80:81], v[144:145], v[164:165]
	v_pk_fma_f32 v[82:83], v[82:83], v[146:147], v[166:167]
	v_cvt_pk_f16_f32 v230, v80, v81
	v_cvt_pk_f16_f32 v231, v82, v83
	s_nop 1
	v_permlane16_swap_b32_e32 v228, v230
	v_permlane16_swap_b32_e32 v229, v231
	global_store_dwordx4 v177, v[228:231], s[80:81] offset:64
	v_add_u32_e32 v177, 0x8000, v177
	v_add_u32_e32 v178, 0x8000, v178
	global_load_dwordx4 v[184:187], v178, s[80:81]
	global_load_dwordx4 v[188:191], v178, s[80:81] offset:64
	s_waitcnt vmcnt(5)
	v_permlane16_swap_b32_e32 v238, v240
	v_permlane16_swap_b32_e32 v239, v241
	v_cvt_f32_f16_e32 v164, v238
	v_cvt_f32_f16_sdwa v165, v238 dst_sel:DWORD dst_unused:UNUSED_PAD src0_sel:WORD_1
	v_cvt_f32_f16_e32 v166, v239
	v_cvt_f32_f16_sdwa v167, v239 dst_sel:DWORD dst_unused:UNUSED_PAD src0_sel:WORD_1
	v_pk_mul_f32 v[164:165], v[164:165], s[84:85] op_sel_hi:[1,0]
	v_pk_mul_f32 v[166:167], v[166:167], s[84:85] op_sel_hi:[1,0]
	v_pk_fma_f32 v[84:85], v[84:85], v[132:133], v[164:165]
	v_pk_fma_f32 v[86:87], v[86:87], v[134:135], v[166:167]
	v_cvt_pk_f16_f32 v172, v84, v85
	v_cvt_pk_f16_f32 v173, v86, v87
	v_cvt_f32_f16_e32 v164, v240
	v_cvt_f32_f16_sdwa v165, v240 dst_sel:DWORD dst_unused:UNUSED_PAD src0_sel:WORD_1
	v_cvt_f32_f16_e32 v166, v241
	v_cvt_f32_f16_sdwa v167, v241 dst_sel:DWORD dst_unused:UNUSED_PAD src0_sel:WORD_1
	v_pk_mul_f32 v[164:165], v[164:165], s[84:85] op_sel_hi:[1,0]
	v_pk_mul_f32 v[166:167], v[166:167], s[84:85] op_sel_hi:[1,0]
	v_pk_fma_f32 v[88:89], v[88:89], v[136:137], v[164:165]
	v_pk_fma_f32 v[90:91], v[90:91], v[138:139], v[166:167]
	v_cvt_pk_f16_f32 v174, v88, v89
	v_cvt_pk_f16_f32 v175, v90, v91
	s_nop 1
	v_permlane16_swap_b32_e32 v172, v174
	v_permlane16_swap_b32_e32 v173, v175
	global_store_dwordx4 v177, v[172:175], s[80:81]
	s_waitcnt vmcnt(5)
	v_permlane16_swap_b32_e32 v242, v244
	v_permlane16_swap_b32_e32 v243, v245
	v_cvt_f32_f16_e32 v164, v242
	v_cvt_f32_f16_sdwa v165, v242 dst_sel:DWORD dst_unused:UNUSED_PAD src0_sel:WORD_1
	v_cvt_f32_f16_e32 v166, v243
	v_cvt_f32_f16_sdwa v167, v243 dst_sel:DWORD dst_unused:UNUSED_PAD src0_sel:WORD_1
	v_pk_mul_f32 v[164:165], v[164:165], s[84:85] op_sel_hi:[1,0]
	v_pk_mul_f32 v[166:167], v[166:167], s[84:85] op_sel_hi:[1,0]
	v_pk_fma_f32 v[92:93], v[92:93], v[140:141], v[164:165]
	v_pk_fma_f32 v[94:95], v[94:95], v[142:143], v[166:167]
	v_cvt_pk_f16_f32 v228, v92, v93
	v_cvt_pk_f16_f32 v229, v94, v95
	v_cvt_f32_f16_e32 v164, v244
	v_cvt_f32_f16_sdwa v165, v244 dst_sel:DWORD dst_unused:UNUSED_PAD src0_sel:WORD_1
	v_cvt_f32_f16_e32 v166, v245
	v_cvt_f32_f16_sdwa v167, v245 dst_sel:DWORD dst_unused:UNUSED_PAD src0_sel:WORD_1
	v_pk_mul_f32 v[164:165], v[164:165], s[84:85] op_sel_hi:[1,0]
	v_pk_mul_f32 v[166:167], v[166:167], s[84:85] op_sel_hi:[1,0]
	v_pk_fma_f32 v[96:97], v[96:97], v[144:145], v[164:165]
	v_pk_fma_f32 v[98:99], v[98:99], v[146:147], v[166:167]
	v_cvt_pk_f16_f32 v230, v96, v97
	v_cvt_pk_f16_f32 v231, v98, v99
	s_nop 1
	v_permlane16_swap_b32_e32 v228, v230
	v_permlane16_swap_b32_e32 v229, v231
	global_store_dwordx4 v177, v[228:231], s[80:81] offset:64
	v_add_u32_e32 v177, 0x8000, v177
	v_add_u32_e32 v178, 0x8000, v178
	global_load_dwordx4 v[238:241], v178, s[80:81]
	global_load_dwordx4 v[242:245], v178, s[80:81] offset:64
	s_waitcnt vmcnt(5)
	v_permlane16_swap_b32_e32 v184, v186
	v_permlane16_swap_b32_e32 v185, v187
	v_cvt_f32_f16_e32 v164, v184
	v_cvt_f32_f16_sdwa v165, v184 dst_sel:DWORD dst_unused:UNUSED_PAD src0_sel:WORD_1
	v_cvt_f32_f16_e32 v166, v185
	v_cvt_f32_f16_sdwa v167, v185 dst_sel:DWORD dst_unused:UNUSED_PAD src0_sel:WORD_1
	v_pk_mul_f32 v[164:165], v[164:165], s[84:85] op_sel_hi:[1,0]
	v_pk_mul_f32 v[166:167], v[166:167], s[84:85] op_sel_hi:[1,0]
	v_pk_fma_f32 v[100:101], v[100:101], v[132:133], v[164:165]
	v_pk_fma_f32 v[102:103], v[102:103], v[134:135], v[166:167]
	v_cvt_pk_f16_f32 v172, v100, v101
	v_cvt_pk_f16_f32 v173, v102, v103
	v_cvt_f32_f16_e32 v164, v186
	v_cvt_f32_f16_sdwa v165, v186 dst_sel:DWORD dst_unused:UNUSED_PAD src0_sel:WORD_1
	v_cvt_f32_f16_e32 v166, v187
	v_cvt_f32_f16_sdwa v167, v187 dst_sel:DWORD dst_unused:UNUSED_PAD src0_sel:WORD_1
	v_pk_mul_f32 v[164:165], v[164:165], s[84:85] op_sel_hi:[1,0]
	v_pk_mul_f32 v[166:167], v[166:167], s[84:85] op_sel_hi:[1,0]
	v_pk_fma_f32 v[104:105], v[104:105], v[136:137], v[164:165]
	v_pk_fma_f32 v[106:107], v[106:107], v[138:139], v[166:167]
	v_cvt_pk_f16_f32 v174, v104, v105
	v_cvt_pk_f16_f32 v175, v106, v107
	s_nop 1
	v_permlane16_swap_b32_e32 v172, v174
	v_permlane16_swap_b32_e32 v173, v175
	global_store_dwordx4 v177, v[172:175], s[80:81]
	s_waitcnt vmcnt(5)
	v_permlane16_swap_b32_e32 v188, v190
	v_permlane16_swap_b32_e32 v189, v191
	v_cvt_f32_f16_e32 v164, v188
	v_cvt_f32_f16_sdwa v165, v188 dst_sel:DWORD dst_unused:UNUSED_PAD src0_sel:WORD_1
	v_cvt_f32_f16_e32 v166, v189
	v_cvt_f32_f16_sdwa v167, v189 dst_sel:DWORD dst_unused:UNUSED_PAD src0_sel:WORD_1
	v_pk_mul_f32 v[164:165], v[164:165], s[84:85] op_sel_hi:[1,0]
	v_pk_mul_f32 v[166:167], v[166:167], s[84:85] op_sel_hi:[1,0]
	v_pk_fma_f32 v[108:109], v[108:109], v[140:141], v[164:165]
	v_pk_fma_f32 v[110:111], v[110:111], v[142:143], v[166:167]
	v_cvt_pk_f16_f32 v228, v108, v109
	v_cvt_pk_f16_f32 v229, v110, v111
	v_cvt_f32_f16_e32 v164, v190
	v_cvt_f32_f16_sdwa v165, v190 dst_sel:DWORD dst_unused:UNUSED_PAD src0_sel:WORD_1
	v_cvt_f32_f16_e32 v166, v191
	v_cvt_f32_f16_sdwa v167, v191 dst_sel:DWORD dst_unused:UNUSED_PAD src0_sel:WORD_1
	v_pk_mul_f32 v[164:165], v[164:165], s[84:85] op_sel_hi:[1,0]
	v_pk_mul_f32 v[166:167], v[166:167], s[84:85] op_sel_hi:[1,0]
	v_pk_fma_f32 v[112:113], v[112:113], v[144:145], v[164:165]
	v_pk_fma_f32 v[114:115], v[114:115], v[146:147], v[166:167]
	v_cvt_pk_f16_f32 v230, v112, v113
	v_cvt_pk_f16_f32 v231, v114, v115
	s_nop 1
	v_permlane16_swap_b32_e32 v228, v230
	v_permlane16_swap_b32_e32 v229, v231
	global_store_dwordx4 v177, v[228:231], s[80:81] offset:64
	v_add_u32_e32 v177, 0x8000, v177
	s_waitcnt vmcnt(3)
	v_permlane16_swap_b32_e32 v238, v240
	v_permlane16_swap_b32_e32 v239, v241
	v_cvt_f32_f16_e32 v164, v238
	v_cvt_f32_f16_sdwa v165, v238 dst_sel:DWORD dst_unused:UNUSED_PAD src0_sel:WORD_1
	v_cvt_f32_f16_e32 v166, v239
	v_cvt_f32_f16_sdwa v167, v239 dst_sel:DWORD dst_unused:UNUSED_PAD src0_sel:WORD_1
	v_pk_mul_f32 v[164:165], v[164:165], s[84:85] op_sel_hi:[1,0]
	v_pk_mul_f32 v[166:167], v[166:167], s[84:85] op_sel_hi:[1,0]
	v_pk_fma_f32 v[116:117], v[116:117], v[132:133], v[164:165]
	v_pk_fma_f32 v[118:119], v[118:119], v[134:135], v[166:167]
	v_cvt_pk_f16_f32 v172, v116, v117
	v_cvt_pk_f16_f32 v173, v118, v119
	v_cvt_f32_f16_e32 v164, v240
	v_cvt_f32_f16_sdwa v165, v240 dst_sel:DWORD dst_unused:UNUSED_PAD src0_sel:WORD_1
	v_cvt_f32_f16_e32 v166, v241
	v_cvt_f32_f16_sdwa v167, v241 dst_sel:DWORD dst_unused:UNUSED_PAD src0_sel:WORD_1
	v_pk_mul_f32 v[164:165], v[164:165], s[84:85] op_sel_hi:[1,0]
	v_pk_mul_f32 v[166:167], v[166:167], s[84:85] op_sel_hi:[1,0]
	v_pk_fma_f32 v[120:121], v[120:121], v[136:137], v[164:165]
	v_pk_fma_f32 v[122:123], v[122:123], v[138:139], v[166:167]
	v_cvt_pk_f16_f32 v174, v120, v121
	v_cvt_pk_f16_f32 v175, v122, v123
	s_nop 1
	v_permlane16_swap_b32_e32 v172, v174
	v_permlane16_swap_b32_e32 v173, v175
	global_store_dwordx4 v177, v[172:175], s[80:81]
	s_waitcnt vmcnt(3)
	v_permlane16_swap_b32_e32 v242, v244
	v_permlane16_swap_b32_e32 v243, v245
	v_cvt_f32_f16_e32 v164, v242
	v_cvt_f32_f16_sdwa v165, v242 dst_sel:DWORD dst_unused:UNUSED_PAD src0_sel:WORD_1
	v_cvt_f32_f16_e32 v166, v243
	v_cvt_f32_f16_sdwa v167, v243 dst_sel:DWORD dst_unused:UNUSED_PAD src0_sel:WORD_1
	v_pk_mul_f32 v[164:165], v[164:165], s[84:85] op_sel_hi:[1,0]
	v_pk_mul_f32 v[166:167], v[166:167], s[84:85] op_sel_hi:[1,0]
	v_pk_fma_f32 v[124:125], v[124:125], v[140:141], v[164:165]
	v_pk_fma_f32 v[126:127], v[126:127], v[142:143], v[166:167]
	v_cvt_pk_f16_f32 v228, v124, v125
	v_cvt_pk_f16_f32 v229, v126, v127
	v_cvt_f32_f16_e32 v164, v244
	v_cvt_f32_f16_sdwa v165, v244 dst_sel:DWORD dst_unused:UNUSED_PAD src0_sel:WORD_1
	v_cvt_f32_f16_e32 v166, v245
	v_cvt_f32_f16_sdwa v167, v245 dst_sel:DWORD dst_unused:UNUSED_PAD src0_sel:WORD_1
	v_pk_mul_f32 v[164:165], v[164:165], s[84:85] op_sel_hi:[1,0]
	v_pk_mul_f32 v[166:167], v[166:167], s[84:85] op_sel_hi:[1,0]
	v_pk_fma_f32 v[128:129], v[128:129], v[144:145], v[164:165]
	v_pk_fma_f32 v[130:131], v[130:131], v[146:147], v[166:167]
	v_cvt_pk_f16_f32 v230, v128, v129
	v_cvt_pk_f16_f32 v231, v130, v131
	s_nop 1
	v_permlane16_swap_b32_e32 v228, v230
	v_permlane16_swap_b32_e32 v229, v231
	global_store_dwordx4 v177, v[228:231], s[80:81] offset:64
	s_nop 1
	s_branch .LBB0_743

.LBB0_1266:
	s_andn2_b64 vcc, exec, s[28:29]
	s_cbranch_vccnz .LBB0_1282
	v_readlane_b32 s26, v236, 3
	v_readlane_b32 s27, v236, 4
	s_andn2_b64 vcc, exec, s[26:27]
	s_cbranch_vccnz .LBB0_1289
	s_add_u32 s26, s44, 0xfa0b600
	s_addc_u32 s27, s45, 0
	v_readlane_b32 s34, v235, 43
	v_readlane_b32 s35, v236, 5
	v_readlane_b32 s36, v236, 9
	s_lshr_b32 s28, s36, 2
	s_lshl_b32 s28, s28, 3
	s_and_b32 s36, s36, 3
	s_lshl_b32 s36, s36, 1
	s_or_b32 s36, s36, s28
	s_branch .LBB0_1270
.LBB0_1270:
	s_and_b32 s50, s36, 56
	s_or_b32 s50, s50, s83
	s_lshl_b32 s50, s50, 8
	s_and_b32 s37, s36, 7
	s_lshl_b32 s37, s37, 7
	s_lshl_b32 s54, s50, 11
	s_add_u32 s28, s48, s54
	s_addc_u32 s29, s49, 0
	s_lshl_b32 s54, s37, 11
	s_add_u32 s30, s46, s54
	s_addc_u32 s31, s47, 0
	v_readfirstlane_b32 s54, v200
	s_lshr_b32 s54, s54, 6
	s_lshl_b32 s32, s54, 11
	s_add_u32 s32, s32, 16
	s_lshl_b32 s54, s54, 16
	s_add_u32 s28, s28, s54
	s_addc_u32 s29, s29, 0
	s_add_u32 s30, s30, s54
	s_addc_u32 s31, s31, 0
	v_bfe_u32 v173, v200, 4, 2
	v_sub_u32_e32 v173, 0, v173
	v_and_b32_e32 v173, 3, v173
	v_and_b32_e32 v172, 3, v200
	v_xor_b32_e32 v172, v172, v173
	v_bfe_u32 v173, v200, 2, 4
	v_lshlrev_b32_e32 v173, 11, v173
	v_lshl_or_b32 v170, v172, 4, v173
	v_add_u32_e32 v171, 0x8000, v170
	v_bfe_u32 v172, v200, 2, 2
	v_sub_u32_e32 v172, 0, v172
	v_and_b32_e32 v172, 3, v172
	v_bfe_u32 v173, v200, 4, 2
	v_xor_b32_e32 v172, v172, v173
	v_and_b32_e32 v173, 15, v200
	v_bfe_u32 v174, v200, 8, 1
	v_lshl_or_b32 v174, v174, 7, v173
	v_lshlrev_b32_e32 v174, 6, v174
	v_lshl_or_b32 v164, v172, 4, v174
	v_bfe_u32 v174, v200, 6, 2
	v_lshl_or_b32 v174, v174, 6, v173
	v_lshlrev_b32_e32 v174, 6, v174
	v_lshl_or_b32 v165, v172, 4, v174
	v_add_u32_e32 v165, 0x4000, v165
	v_bfe_u32 v172, v200, 6, 2
	v_bfe_u32 v173, v200, 4, 2
	v_lshlrev_b32_e32 v172, 6, v172
	v_lshl_or_b32 v172, v173, 2, v172
	v_add_u32_e32 v172, s37, v172
	v_lshlrev_b32_e32 v172, 2, v172
	global_load_dwordx4 v[132:135], v172, s[24:25]
	global_load_dwordx4 v[136:139], v172, s[24:25] offset:64
	global_load_dwordx4 v[140:143], v172, s[24:25] offset:128
	global_load_dwordx4 v[144:147], v172, s[24:25] offset:192
	s_mov_b32 s52, s32
	s_mov_b32 m0, s52
	s_nop 0
	global_load_lds_dwordx4 v170, s[28:29]
	s_add_u32 m0, s52, 0x400
	s_nop 0
	global_load_lds_dwordx4 v171, s[28:29]
	s_add_u32 m0, s52, 0x4000
	s_nop 0
	global_load_lds_dwordx4 v170, s[30:31]
	s_add_u32 m0, s52, 0x4400
	s_nop 0
	global_load_lds_dwordx4 v171, s[30:31]
	s_add_u32 s28, s28, 64
	s_addc_u32 s29, s29, 0
	s_add_u32 s30, s30, 64
	s_addc_u32 s31, s31, 0
	s_add_u32 s52, s32, 0x8000
	s_mov_b32 m0, s52
	s_nop 0
	global_load_lds_dwordx4 v170, s[28:29]
	s_add_u32 m0, s52, 0x400
	s_nop 0
	global_load_lds_dwordx4 v171, s[28:29]
	s_add_u32 m0, s52, 0x4000
	s_nop 0
	global_load_lds_dwordx4 v170, s[30:31]
	s_add_u32 m0, s52, 0x4400
	s_nop 0
	global_load_lds_dwordx4 v171, s[30:31]
	s_add_u32 s28, s28, 64
	s_addc_u32 s29, s29, 0
	s_add_u32 s30, s30, 64
	s_addc_u32 s31, s31, 0
	s_add_u32 s52, s32, 0x10000
	s_mov_b32 m0, s52
	s_nop 0
	global_load_lds_dwordx4 v170, s[28:29]
	s_add_u32 m0, s52, 0x400
	s_nop 0
	global_load_lds_dwordx4 v171, s[28:29]
	s_add_u32 m0, s52, 0x4000
	s_nop 0
	global_load_lds_dwordx4 v170, s[30:31]
	s_add_u32 m0, s52, 0x4400
	s_nop 0
	global_load_lds_dwordx4 v171, s[30:31]
	s_add_u32 s28, s28, 64
	s_addc_u32 s29, s29, 0
	s_add_u32 s30, s30, 64
	s_addc_u32 s31, s31, 0
	s_add_u32 s52, s32, 0x18000
	s_mov_b32 m0, s52
	s_nop 0
	global_load_lds_dwordx4 v170, s[28:29]
	s_add_u32 m0, s52, 0x400
	s_nop 0
	global_load_lds_dwordx4 v171, s[28:29]
	s_add_u32 m0, s52, 0x4000
	s_nop 0
	global_load_lds_dwordx4 v170, s[30:31]
	s_add_u32 m0, s52, 0x4400
	s_nop 0
	global_load_lds_dwordx4 v171, s[30:31]
	s_add_u32 s28, s28, 64
	s_addc_u32 s29, s29, 0
	s_add_u32 s30, s30, 64
	s_addc_u32 s31, s31, 0
	s_waitcnt vmcnt(16)
	v_mov_b32_e32 v4, v132
	v_mov_b32_e32 v5, v133
	v_mov_b32_e32 v6, v134
	v_mov_b32_e32 v7, v135
	v_mov_b32_e32 v8, v136
	v_mov_b32_e32 v9, v137
	v_mov_b32_e32 v10, v138
	v_mov_b32_e32 v11, v139
	v_mov_b32_e32 v12, v140
	v_mov_b32_e32 v13, v141
	v_mov_b32_e32 v14, v142
	v_mov_b32_e32 v15, v143
	v_mov_b32_e32 v16, v144
	v_mov_b32_e32 v17, v145
	v_mov_b32_e32 v18, v146
	v_mov_b32_e32 v19, v147
	v_mov_b32_e32 v20, v132
	v_mov_b32_e32 v21, v133
	v_mov_b32_e32 v22, v134
	v_mov_b32_e32 v23, v135
	v_mov_b32_e32 v24, v136
	v_mov_b32_e32 v25, v137
	v_mov_b32_e32 v26, v138
	v_mov_b32_e32 v27, v139
	v_mov_b32_e32 v28, v140
	v_mov_b32_e32 v29, v141
	v_mov_b32_e32 v30, v142
	v_mov_b32_e32 v31, v143
	v_mov_b32_e32 v32, v144
	v_mov_b32_e32 v33, v145
	v_mov_b32_e32 v34, v146
	v_mov_b32_e32 v35, v147
	v_mov_b32_e32 v36, v132
	v_mov_b32_e32 v37, v133
	v_mov_b32_e32 v38, v134
	v_mov_b32_e32 v39, v135
	v_mov_b32_e32 v40, v136
	v_mov_b32_e32 v41, v137
	v_mov_b32_e32 v42, v138
	v_mov_b32_e32 v43, v139
	v_mov_b32_e32 v44, v140
	v_mov_b32_e32 v45, v141
	v_mov_b32_e32 v46, v142
	v_mov_b32_e32 v47, v143
	v_mov_b32_e32 v48, v144
	v_mov_b32_e32 v49, v145
	v_mov_b32_e32 v50, v146
	v_mov_b32_e32 v51, v147
	v_mov_b32_e32 v52, v132
	v_mov_b32_e32 v53, v133
	v_mov_b32_e32 v54, v134
	v_mov_b32_e32 v55, v135
	v_mov_b32_e32 v56, v136
	v_mov_b32_e32 v57, v137
	v_mov_b32_e32 v58, v138
	v_mov_b32_e32 v59, v139
	v_mov_b32_e32 v60, v140
	v_mov_b32_e32 v61, v141
	v_mov_b32_e32 v62, v142
	v_mov_b32_e32 v63, v143
	v_mov_b32_e32 v64, v144
	v_mov_b32_e32 v65, v145
	v_mov_b32_e32 v66, v146
	v_mov_b32_e32 v67, v147
	v_mov_b32_e32 v68, v132
	v_mov_b32_e32 v69, v133
	v_mov_b32_e32 v70, v134
	v_mov_b32_e32 v71, v135
	v_mov_b32_e32 v72, v136
	v_mov_b32_e32 v73, v137
	v_mov_b32_e32 v74, v138
	v_mov_b32_e32 v75, v139
	v_mov_b32_e32 v76, v140
	v_mov_b32_e32 v77, v141
	v_mov_b32_e32 v78, v142
	v_mov_b32_e32 v79, v143
	v_mov_b32_e32 v80, v144
	v_mov_b32_e32 v81, v145
	v_mov_b32_e32 v82, v146
	v_mov_b32_e32 v83, v147
	v_mov_b32_e32 v84, v132
	v_mov_b32_e32 v85, v133
	v_mov_b32_e32 v86, v134
	v_mov_b32_e32 v87, v135
	v_mov_b32_e32 v88, v136
	v_mov_b32_e32 v89, v137
	v_mov_b32_e32 v90, v138
	v_mov_b32_e32 v91, v139
	v_mov_b32_e32 v92, v140
	v_mov_b32_e32 v93, v141
	v_mov_b32_e32 v94, v142
	v_mov_b32_e32 v95, v143
	v_mov_b32_e32 v96, v144
	v_mov_b32_e32 v97, v145
	v_mov_b32_e32 v98, v146
	v_mov_b32_e32 v99, v147
	v_mov_b32_e32 v100, v132
	v_mov_b32_e32 v101, v133
	v_mov_b32_e32 v102, v134
	v_mov_b32_e32 v103, v135
	v_mov_b32_e32 v104, v136
	v_mov_b32_e32 v105, v137
	v_mov_b32_e32 v106, v138
	v_mov_b32_e32 v107, v139
	v_mov_b32_e32 v108, v140
	v_mov_b32_e32 v109, v141
	v_mov_b32_e32 v110, v142
	v_mov_b32_e32 v111, v143
	v_mov_b32_e32 v112, v144
	v_mov_b32_e32 v113, v145
	v_mov_b32_e32 v114, v146
	v_mov_b32_e32 v115, v147
	v_mov_b32_e32 v116, v132
	v_mov_b32_e32 v117, v133
	v_mov_b32_e32 v118, v134
	v_mov_b32_e32 v119, v135
	v_mov_b32_e32 v120, v136
	v_mov_b32_e32 v121, v137
	v_mov_b32_e32 v122, v138
	v_mov_b32_e32 v123, v139
	v_mov_b32_e32 v124, v140
	v_mov_b32_e32 v125, v141
	v_mov_b32_e32 v126, v142
	v_mov_b32_e32 v127, v143
	v_mov_b32_e32 v128, v144
	v_mov_b32_e32 v129, v145
	v_mov_b32_e32 v130, v146
	v_mov_b32_e32 v131, v147
	s_waitcnt vmcnt(12)
	s_barrier
	s_mov_b32 s51, 0
	s_mov_b32 s53, 0
	s_nop 1
	v_add_u32_e32 v168, s51, v165
	v_add_u32_e32 v169, s51, v164
	ds_read_b128 v[132:135], v168 offset:16
	ds_read_b128 v[136:139], v168 offset:1040
	ds_read_b128 v[140:143], v168 offset:2064
	ds_read_b128 v[144:147], v168 offset:3088
	ds_read_b128 v[184:187], v169 offset:16
	ds_read_b128 v[188:191], v169 offset:1040
	ds_read_b128 v[192:195], v169 offset:2064
	ds_read_b128 v[196:199], v169 offset:3088
	s_waitcnt lgkmcnt(0)
.Lt_out0:
	v_add_u32_e32 v169, s51, v164
	v_mfma_f32_16x16x32_f16 v[4:7], v[132:135], v[184:187], v[4:7]
	ds_read_b128 v[238:241], v169 offset:4112
	v_mfma_f32_16x16x32_f16 v[8:11], v[136:139], v[184:187], v[8:11]
	ds_read_b128 v[242:245], v169 offset:5136
	v_mfma_f32_16x16x32_f16 v[12:15], v[140:143], v[184:187], v[12:15]
	ds_read_b128 v[246:249], v169 offset:6160
	v_mfma_f32_16x16x32_f16 v[16:19], v[144:147], v[184:187], v[16:19]
	ds_read_b128 v[250:253], v169 offset:7184
	v_mfma_f32_16x16x32_f16 v[20:23], v[132:135], v[188:191], v[20:23]
	v_mfma_f32_16x16x32_f16 v[24:27], v[136:139], v[188:191], v[24:27]
	v_mfma_f32_16x16x32_f16 v[28:31], v[140:143], v[188:191], v[28:31]
	v_mfma_f32_16x16x32_f16 v[32:35], v[144:147], v[188:191], v[32:35]
	v_mfma_f32_16x16x32_f16 v[36:39], v[132:135], v[192:195], v[36:39]
	v_mfma_f32_16x16x32_f16 v[40:43], v[136:139], v[192:195], v[40:43]
	v_mfma_f32_16x16x32_f16 v[44:47], v[140:143], v[192:195], v[44:47]
	v_mfma_f32_16x16x32_f16 v[48:51], v[144:147], v[192:195], v[48:51]
	v_mfma_f32_16x16x32_f16 v[52:55], v[132:135], v[196:199], v[52:55]
	v_mfma_f32_16x16x32_f16 v[56:59], v[136:139], v[196:199], v[56:59]
	v_mfma_f32_16x16x32_f16 v[60:63], v[140:143], v[196:199], v[60:63]
	v_mfma_f32_16x16x32_f16 v[64:67], v[144:147], v[196:199], v[64:67]
	s_waitcnt vmcnt(8) lgkmcnt(0)
	s_barrier
	s_add_i32 s52, s51, 0x8000
	s_cmp_lg_u32 s51, 0x18000
	s_cselect_b32 s52, s52, 0
	v_add_u32_e32 v168, s52, v165
	v_add_u32_e32 v169, s52, v164
	s_add_u32 vcc_lo, s32, s51
	v_mfma_f32_16x16x32_f16 v[68:71], v[132:135], v[238:241], v[68:71]
	ds_read_b128 v[148:151], v168 offset:16
	ds_read_b128 v[184:187], v169 offset:16
	v_mfma_f32_16x16x32_f16 v[72:75], v[136:139], v[238:241], v[72:75]
	ds_read_b128 v[152:155], v168 offset:1040
	ds_read_b128 v[188:191], v169 offset:1040
	v_mfma_f32_16x16x32_f16 v[76:79], v[140:143], v[238:241], v[76:79]
	ds_read_b128 v[156:159], v168 offset:2064
	ds_read_b128 v[192:195], v169 offset:2064
	v_mfma_f32_16x16x32_f16 v[80:83], v[144:147], v[238:241], v[80:83]
	ds_read_b128 v[160:163], v168 offset:3088
	ds_read_b128 v[196:199], v169 offset:3088
	v_mfma_f32_16x16x32_f16 v[84:87], v[132:135], v[242:245], v[84:87]
	v_mfma_f32_16x16x32_f16 v[88:91], v[136:139], v[242:245], v[88:91]
	v_mfma_f32_16x16x32_f16 v[92:95], v[140:143], v[242:245], v[92:95]
	v_mfma_f32_16x16x32_f16 v[96:99], v[144:147], v[242:245], v[96:99]
	v_mfma_f32_16x16x32_f16 v[100:103], v[132:135], v[246:249], v[100:103]
	s_mov_b32 m0, vcc_lo
	s_nop 0
	global_load_lds_dwordx4 v170, s[28:29]
	v_mfma_f32_16x16x32_f16 v[104:107], v[136:139], v[246:249], v[104:107]
	s_add_u32 m0, vcc_lo, 0x400
	s_nop 0
	global_load_lds_dwordx4 v171, s[28:29]
	v_mfma_f32_16x16x32_f16 v[108:111], v[140:143], v[246:249], v[108:111]
	s_add_u32 m0, vcc_lo, 0x4000
	s_nop 0
	global_load_lds_dwordx4 v170, s[30:31]
	v_mfma_f32_16x16x32_f16 v[112:115], v[144:147], v[246:249], v[112:115]
	s_add_u32 m0, vcc_lo, 0x4400
	s_nop 0
	global_load_lds_dwordx4 v171, s[30:31]
	v_mfma_f32_16x16x32_f16 v[116:119], v[132:135], v[250:253], v[116:119]
	v_mfma_f32_16x16x32_f16 v[120:123], v[136:139], v[250:253], v[120:123]
	v_mfma_f32_16x16x32_f16 v[124:127], v[140:143], v[250:253], v[124:127]
	v_mfma_f32_16x16x32_f16 v[128:131], v[144:147], v[250:253], v[128:131]
	s_waitcnt lgkmcnt(0)
	s_mov_b32 s51, s52
	s_add_u32 s28, s28, 64
	s_addc_u32 s29, s29, 0
	s_add_u32 s30, s30, 64
	s_addc_u32 s31, s31, 0
	v_add_u32_e32 v169, s51, v164
	v_mfma_f32_16x16x32_f16 v[4:7], v[148:151], v[184:187], v[4:7]
	ds_read_b128 v[238:241], v169 offset:4112
	v_mfma_f32_16x16x32_f16 v[8:11], v[152:155], v[184:187], v[8:11]
	ds_read_b128 v[242:245], v169 offset:5136
	v_mfma_f32_16x16x32_f16 v[12:15], v[156:159], v[184:187], v[12:15]
	ds_read_b128 v[246:249], v169 offset:6160
	v_mfma_f32_16x16x32_f16 v[16:19], v[160:163], v[184:187], v[16:19]
	ds_read_b128 v[250:253], v169 offset:7184
	v_mfma_f32_16x16x32_f16 v[20:23], v[148:151], v[188:191], v[20:23]
	v_mfma_f32_16x16x32_f16 v[24:27], v[152:155], v[188:191], v[24:27]
	v_mfma_f32_16x16x32_f16 v[28:31], v[156:159], v[188:191], v[28:31]
	v_mfma_f32_16x16x32_f16 v[32:35], v[160:163], v[188:191], v[32:35]
	v_mfma_f32_16x16x32_f16 v[36:39], v[148:151], v[192:195], v[36:39]
	v_mfma_f32_16x16x32_f16 v[40:43], v[152:155], v[192:195], v[40:43]
	v_mfma_f32_16x16x32_f16 v[44:47], v[156:159], v[192:195], v[44:47]
	v_mfma_f32_16x16x32_f16 v[48:51], v[160:163], v[192:195], v[48:51]
	v_mfma_f32_16x16x32_f16 v[52:55], v[148:151], v[196:199], v[52:55]
	v_mfma_f32_16x16x32_f16 v[56:59], v[152:155], v[196:199], v[56:59]
	v_mfma_f32_16x16x32_f16 v[60:63], v[156:159], v[196:199], v[60:63]
	v_mfma_f32_16x16x32_f16 v[64:67], v[160:163], v[196:199], v[64:67]
	s_waitcnt vmcnt(8) lgkmcnt(0)
	s_barrier
	s_add_i32 s52, s51, 0x8000
	s_cmp_lg_u32 s51, 0x18000
	s_cselect_b32 s52, s52, 0
	v_add_u32_e32 v168, s52, v165
	v_add_u32_e32 v169, s52, v164
	s_add_u32 vcc_lo, s32, s51
	v_mfma_f32_16x16x32_f16 v[68:71], v[148:151], v[238:241], v[68:71]
	ds_read_b128 v[132:135], v168 offset:16
	ds_read_b128 v[184:187], v169 offset:16
	v_mfma_f32_16x16x32_f16 v[72:75], v[152:155], v[238:241], v[72:75]
	ds_read_b128 v[136:139], v168 offset:1040
	ds_read_b128 v[188:191], v169 offset:1040
	v_mfma_f32_16x16x32_f16 v[76:79], v[156:159], v[238:241], v[76:79]
	ds_read_b128 v[140:143], v168 offset:2064
	ds_read_b128 v[192:195], v169 offset:2064
	v_mfma_f32_16x16x32_f16 v[80:83], v[160:163], v[238:241], v[80:83]
	ds_read_b128 v[144:147], v168 offset:3088
	ds_read_b128 v[196:199], v169 offset:3088
	v_mfma_f32_16x16x32_f16 v[84:87], v[148:151], v[242:245], v[84:87]
	v_mfma_f32_16x16x32_f16 v[88:91], v[152:155], v[242:245], v[88:91]
	v_mfma_f32_16x16x32_f16 v[92:95], v[156:159], v[242:245], v[92:95]
	v_mfma_f32_16x16x32_f16 v[96:99], v[160:163], v[242:245], v[96:99]
	v_mfma_f32_16x16x32_f16 v[100:103], v[148:151], v[246:249], v[100:103]
	s_mov_b32 m0, vcc_lo
	s_nop 0
	global_load_lds_dwordx4 v170, s[28:29]
	v_mfma_f32_16x16x32_f16 v[104:107], v[152:155], v[246:249], v[104:107]
	s_add_u32 m0, vcc_lo, 0x400
	s_nop 0
	global_load_lds_dwordx4 v171, s[28:29]
	v_mfma_f32_16x16x32_f16 v[108:111], v[156:159], v[246:249], v[108:111]
	s_add_u32 m0, vcc_lo, 0x4000
	s_nop 0
	global_load_lds_dwordx4 v170, s[30:31]
	v_mfma_f32_16x16x32_f16 v[112:115], v[160:163], v[246:249], v[112:115]
	s_add_u32 m0, vcc_lo, 0x4400
	s_nop 0
	global_load_lds_dwordx4 v171, s[30:31]
	v_mfma_f32_16x16x32_f16 v[116:119], v[148:151], v[250:253], v[116:119]
	v_mfma_f32_16x16x32_f16 v[120:123], v[152:155], v[250:253], v[120:123]
	v_mfma_f32_16x16x32_f16 v[124:127], v[156:159], v[250:253], v[124:127]
	v_mfma_f32_16x16x32_f16 v[128:131], v[160:163], v[250:253], v[128:131]
	s_waitcnt lgkmcnt(0)
	s_mov_b32 s51, s52
	s_add_u32 s28, s28, 64
	s_addc_u32 s29, s29, 0
	s_add_u32 s30, s30, 64
	s_addc_u32 s31, s31, 0
	s_add_i32 s53, s53, 2
	s_cmp_lt_u32 s53, 28
	s_cbranch_scc1 .Lt_out0
	v_add_u32_e32 v169, s51, v164
	v_mfma_f32_16x16x32_f16 v[4:7], v[132:135], v[184:187], v[4:7]
	ds_read_b128 v[238:241], v169 offset:4112
	v_mfma_f32_16x16x32_f16 v[8:11], v[136:139], v[184:187], v[8:11]
	ds_read_b128 v[242:245], v169 offset:5136
	v_mfma_f32_16x16x32_f16 v[12:15], v[140:143], v[184:187], v[12:15]
	ds_read_b128 v[246:249], v169 offset:6160
	v_mfma_f32_16x16x32_f16 v[16:19], v[144:147], v[184:187], v[16:19]
	ds_read_b128 v[250:253], v169 offset:7184
	v_mfma_f32_16x16x32_f16 v[20:23], v[132:135], v[188:191], v[20:23]
	v_mfma_f32_16x16x32_f16 v[24:27], v[136:139], v[188:191], v[24:27]
	v_mfma_f32_16x16x32_f16 v[28:31], v[140:143], v[188:191], v[28:31]
	v_mfma_f32_16x16x32_f16 v[32:35], v[144:147], v[188:191], v[32:35]
	v_mfma_f32_16x16x32_f16 v[36:39], v[132:135], v[192:195], v[36:39]
	v_mfma_f32_16x16x32_f16 v[40:43], v[136:139], v[192:195], v[40:43]
	v_mfma_f32_16x16x32_f16 v[44:47], v[140:143], v[192:195], v[44:47]
	v_mfma_f32_16x16x32_f16 v[48:51], v[144:147], v[192:195], v[48:51]
	v_mfma_f32_16x16x32_f16 v[52:55], v[132:135], v[196:199], v[52:55]
	v_mfma_f32_16x16x32_f16 v[56:59], v[136:139], v[196:199], v[56:59]
	v_mfma_f32_16x16x32_f16 v[60:63], v[140:143], v[196:199], v[60:63]
	v_mfma_f32_16x16x32_f16 v[64:67], v[144:147], v[196:199], v[64:67]
	s_waitcnt vmcnt(8) lgkmcnt(0)
	s_barrier
	s_add_i32 s52, s51, 0x8000
	s_cmp_lg_u32 s51, 0x18000
	s_cselect_b32 s52, s52, 0
	v_add_u32_e32 v168, s52, v165
	v_add_u32_e32 v169, s52, v164
	v_mfma_f32_16x16x32_f16 v[68:71], v[132:135], v[238:241], v[68:71]
	ds_read_b128 v[148:151], v168 offset:16
	ds_read_b128 v[184:187], v169 offset:16
	v_mfma_f32_16x16x32_f16 v[72:75], v[136:139], v[238:241], v[72:75]
	ds_read_b128 v[152:155], v168 offset:1040
	ds_read_b128 v[188:191], v169 offset:1040
	v_mfma_f32_16x16x32_f16 v[76:79], v[140:143], v[238:241], v[76:79]
	ds_read_b128 v[156:159], v168 offset:2064
	ds_read_b128 v[192:195], v169 offset:2064
	v_mfma_f32_16x16x32_f16 v[80:83], v[144:147], v[238:241], v[80:83]
	ds_read_b128 v[160:163], v168 offset:3088
	ds_read_b128 v[196:199], v169 offset:3088
	v_mfma_f32_16x16x32_f16 v[84:87], v[132:135], v[242:245], v[84:87]
	v_mfma_f32_16x16x32_f16 v[88:91], v[136:139], v[242:245], v[88:91]
	v_mfma_f32_16x16x32_f16 v[92:95], v[140:143], v[242:245], v[92:95]
	v_mfma_f32_16x16x32_f16 v[96:99], v[144:147], v[242:245], v[96:99]
	v_mfma_f32_16x16x32_f16 v[100:103], v[132:135], v[246:249], v[100:103]
	v_mfma_f32_16x16x32_f16 v[104:107], v[136:139], v[246:249], v[104:107]
	v_mfma_f32_16x16x32_f16 v[108:111], v[140:143], v[246:249], v[108:111]
	v_mfma_f32_16x16x32_f16 v[112:115], v[144:147], v[246:249], v[112:115]
	v_mfma_f32_16x16x32_f16 v[116:119], v[132:135], v[250:253], v[116:119]
	v_mfma_f32_16x16x32_f16 v[120:123], v[136:139], v[250:253], v[120:123]
	v_mfma_f32_16x16x32_f16 v[124:127], v[140:143], v[250:253], v[124:127]
	v_mfma_f32_16x16x32_f16 v[128:131], v[144:147], v[250:253], v[128:131]
	s_waitcnt lgkmcnt(0)
	s_mov_b32 s51, s52
	v_add_u32_e32 v169, s51, v164
	v_mfma_f32_16x16x32_f16 v[4:7], v[148:151], v[184:187], v[4:7]
	ds_read_b128 v[238:241], v169 offset:4112
	v_mfma_f32_16x16x32_f16 v[8:11], v[152:155], v[184:187], v[8:11]
	ds_read_b128 v[242:245], v169 offset:5136
	v_mfma_f32_16x16x32_f16 v[12:15], v[156:159], v[184:187], v[12:15]
	ds_read_b128 v[246:249], v169 offset:6160
	v_mfma_f32_16x16x32_f16 v[16:19], v[160:163], v[184:187], v[16:19]
	ds_read_b128 v[250:253], v169 offset:7184
	v_mfma_f32_16x16x32_f16 v[20:23], v[148:151], v[188:191], v[20:23]
	v_mfma_f32_16x16x32_f16 v[24:27], v[152:155], v[188:191], v[24:27]
	v_mfma_f32_16x16x32_f16 v[28:31], v[156:159], v[188:191], v[28:31]
	v_mfma_f32_16x16x32_f16 v[32:35], v[160:163], v[188:191], v[32:35]
	v_mfma_f32_16x16x32_f16 v[36:39], v[148:151], v[192:195], v[36:39]
	v_mfma_f32_16x16x32_f16 v[40:43], v[152:155], v[192:195], v[40:43]
	v_mfma_f32_16x16x32_f16 v[44:47], v[156:159], v[192:195], v[44:47]
	v_mfma_f32_16x16x32_f16 v[48:51], v[160:163], v[192:195], v[48:51]
	v_mfma_f32_16x16x32_f16 v[52:55], v[148:151], v[196:199], v[52:55]
	v_mfma_f32_16x16x32_f16 v[56:59], v[152:155], v[196:199], v[56:59]
	v_mfma_f32_16x16x32_f16 v[60:63], v[156:159], v[196:199], v[60:63]
	v_mfma_f32_16x16x32_f16 v[64:67], v[160:163], v[196:199], v[64:67]
	s_waitcnt vmcnt(4) lgkmcnt(0)
	s_barrier
	s_add_i32 s52, s51, 0x8000
	s_cmp_lg_u32 s51, 0x18000
	s_cselect_b32 s52, s52, 0
	v_add_u32_e32 v168, s52, v165
	v_add_u32_e32 v169, s52, v164
	v_mfma_f32_16x16x32_f16 v[68:71], v[148:151], v[238:241], v[68:71]
	ds_read_b128 v[132:135], v168 offset:16
	ds_read_b128 v[184:187], v169 offset:16
	v_mfma_f32_16x16x32_f16 v[72:75], v[152:155], v[238:241], v[72:75]
	ds_read_b128 v[136:139], v168 offset:1040
	ds_read_b128 v[188:191], v169 offset:1040
	v_mfma_f32_16x16x32_f16 v[76:79], v[156:159], v[238:241], v[76:79]
	ds_read_b128 v[140:143], v168 offset:2064
	ds_read_b128 v[192:195], v169 offset:2064
	v_mfma_f32_16x16x32_f16 v[80:83], v[160:163], v[238:241], v[80:83]
	ds_read_b128 v[144:147], v168 offset:3088
	ds_read_b128 v[196:199], v169 offset:3088
	v_mfma_f32_16x16x32_f16 v[84:87], v[148:151], v[242:245], v[84:87]
	v_mfma_f32_16x16x32_f16 v[88:91], v[152:155], v[242:245], v[88:91]
	v_mfma_f32_16x16x32_f16 v[92:95], v[156:159], v[242:245], v[92:95]
	v_mfma_f32_16x16x32_f16 v[96:99], v[160:163], v[242:245], v[96:99]
	v_mfma_f32_16x16x32_f16 v[100:103], v[148:151], v[246:249], v[100:103]
	v_mfma_f32_16x16x32_f16 v[104:107], v[152:155], v[246:249], v[104:107]
	v_mfma_f32_16x16x32_f16 v[108:111], v[156:159], v[246:249], v[108:111]
	v_mfma_f32_16x16x32_f16 v[112:115], v[160:163], v[246:249], v[112:115]
	v_mfma_f32_16x16x32_f16 v[116:119], v[148:151], v[250:253], v[116:119]
	v_mfma_f32_16x16x32_f16 v[120:123], v[152:155], v[250:253], v[120:123]
	v_mfma_f32_16x16x32_f16 v[124:127], v[156:159], v[250:253], v[124:127]
	v_mfma_f32_16x16x32_f16 v[128:131], v[160:163], v[250:253], v[128:131]
	s_waitcnt lgkmcnt(0)
	s_mov_b32 s51, s52
	v_add_u32_e32 v169, s51, v164
	v_mfma_f32_16x16x32_f16 v[4:7], v[132:135], v[184:187], v[4:7]
	ds_read_b128 v[238:241], v169 offset:4112
	v_mfma_f32_16x16x32_f16 v[8:11], v[136:139], v[184:187], v[8:11]
	ds_read_b128 v[242:245], v169 offset:5136
	v_mfma_f32_16x16x32_f16 v[12:15], v[140:143], v[184:187], v[12:15]
	ds_read_b128 v[246:249], v169 offset:6160
	v_mfma_f32_16x16x32_f16 v[16:19], v[144:147], v[184:187], v[16:19]
	ds_read_b128 v[250:253], v169 offset:7184
	v_mfma_f32_16x16x32_f16 v[20:23], v[132:135], v[188:191], v[20:23]
	v_mfma_f32_16x16x32_f16 v[24:27], v[136:139], v[188:191], v[24:27]
	v_mfma_f32_16x16x32_f16 v[28:31], v[140:143], v[188:191], v[28:31]
	v_mfma_f32_16x16x32_f16 v[32:35], v[144:147], v[188:191], v[32:35]
	v_mfma_f32_16x16x32_f16 v[36:39], v[132:135], v[192:195], v[36:39]
	v_mfma_f32_16x16x32_f16 v[40:43], v[136:139], v[192:195], v[40:43]
	v_mfma_f32_16x16x32_f16 v[44:47], v[140:143], v[192:195], v[44:47]
	v_mfma_f32_16x16x32_f16 v[48:51], v[144:147], v[192:195], v[48:51]
	v_mfma_f32_16x16x32_f16 v[52:55], v[132:135], v[196:199], v[52:55]
	v_mfma_f32_16x16x32_f16 v[56:59], v[136:139], v[196:199], v[56:59]
	v_mfma_f32_16x16x32_f16 v[60:63], v[140:143], v[196:199], v[60:63]
	v_mfma_f32_16x16x32_f16 v[64:67], v[144:147], v[196:199], v[64:67]
	s_waitcnt vmcnt(0) lgkmcnt(0)
	s_barrier
	s_add_i32 s52, s51, 0x8000
	s_cmp_lg_u32 s51, 0x18000
	s_cselect_b32 s52, s52, 0
	v_add_u32_e32 v168, s52, v165
	v_add_u32_e32 v169, s52, v164
	v_mfma_f32_16x16x32_f16 v[68:71], v[132:135], v[238:241], v[68:71]
	ds_read_b128 v[148:151], v168 offset:16
	ds_read_b128 v[184:187], v169 offset:16
	v_mfma_f32_16x16x32_f16 v[72:75], v[136:139], v[238:241], v[72:75]
	ds_read_b128 v[152:155], v168 offset:1040
	ds_read_b128 v[188:191], v169 offset:1040
	v_mfma_f32_16x16x32_f16 v[76:79], v[140:143], v[238:241], v[76:79]
	ds_read_b128 v[156:159], v168 offset:2064
	ds_read_b128 v[192:195], v169 offset:2064
	v_mfma_f32_16x16x32_f16 v[80:83], v[144:147], v[238:241], v[80:83]
	ds_read_b128 v[160:163], v168 offset:3088
	ds_read_b128 v[196:199], v169 offset:3088
	v_mfma_f32_16x16x32_f16 v[84:87], v[132:135], v[242:245], v[84:87]
	v_mfma_f32_16x16x32_f16 v[88:91], v[136:139], v[242:245], v[88:91]
	v_mfma_f32_16x16x32_f16 v[92:95], v[140:143], v[242:245], v[92:95]
	v_mfma_f32_16x16x32_f16 v[96:99], v[144:147], v[242:245], v[96:99]
	v_mfma_f32_16x16x32_f16 v[100:103], v[132:135], v[246:249], v[100:103]
	v_mfma_f32_16x16x32_f16 v[104:107], v[136:139], v[246:249], v[104:107]
	v_mfma_f32_16x16x32_f16 v[108:111], v[140:143], v[246:249], v[108:111]
	v_mfma_f32_16x16x32_f16 v[112:115], v[144:147], v[246:249], v[112:115]
	v_mfma_f32_16x16x32_f16 v[116:119], v[132:135], v[250:253], v[116:119]
	v_mfma_f32_16x16x32_f16 v[120:123], v[136:139], v[250:253], v[120:123]
	v_mfma_f32_16x16x32_f16 v[124:127], v[140:143], v[250:253], v[124:127]
	v_mfma_f32_16x16x32_f16 v[128:131], v[144:147], v[250:253], v[128:131]
	s_waitcnt lgkmcnt(0)
	s_mov_b32 s51, s52
	v_add_u32_e32 v169, s51, v164
	v_mfma_f32_16x16x32_f16 v[4:7], v[148:151], v[184:187], v[4:7]
	ds_read_b128 v[238:241], v169 offset:4112
	v_mfma_f32_16x16x32_f16 v[8:11], v[152:155], v[184:187], v[8:11]
	ds_read_b128 v[242:245], v169 offset:5136
	v_mfma_f32_16x16x32_f16 v[12:15], v[156:159], v[184:187], v[12:15]
	ds_read_b128 v[246:249], v169 offset:6160
	v_mfma_f32_16x16x32_f16 v[16:19], v[160:163], v[184:187], v[16:19]
	ds_read_b128 v[250:253], v169 offset:7184
	v_mfma_f32_16x16x32_f16 v[20:23], v[148:151], v[188:191], v[20:23]
	v_mfma_f32_16x16x32_f16 v[24:27], v[152:155], v[188:191], v[24:27]
	v_mfma_f32_16x16x32_f16 v[28:31], v[156:159], v[188:191], v[28:31]
	v_mfma_f32_16x16x32_f16 v[32:35], v[160:163], v[188:191], v[32:35]
	v_mfma_f32_16x16x32_f16 v[36:39], v[148:151], v[192:195], v[36:39]
	v_mfma_f32_16x16x32_f16 v[40:43], v[152:155], v[192:195], v[40:43]
	v_mfma_f32_16x16x32_f16 v[44:47], v[156:159], v[192:195], v[44:47]
	v_mfma_f32_16x16x32_f16 v[48:51], v[160:163], v[192:195], v[48:51]
	v_mfma_f32_16x16x32_f16 v[52:55], v[148:151], v[196:199], v[52:55]
	v_mfma_f32_16x16x32_f16 v[56:59], v[152:155], v[196:199], v[56:59]
	v_mfma_f32_16x16x32_f16 v[60:63], v[156:159], v[196:199], v[60:63]
	v_mfma_f32_16x16x32_f16 v[64:67], v[160:163], v[196:199], v[64:67]
	s_waitcnt lgkmcnt(0)
	s_barrier
	v_mfma_f32_16x16x32_f16 v[68:71], v[148:151], v[238:241], v[68:71]
	v_mfma_f32_16x16x32_f16 v[72:75], v[152:155], v[238:241], v[72:75]
	v_mfma_f32_16x16x32_f16 v[76:79], v[156:159], v[238:241], v[76:79]
	v_mfma_f32_16x16x32_f16 v[80:83], v[160:163], v[238:241], v[80:83]
	v_mfma_f32_16x16x32_f16 v[84:87], v[148:151], v[242:245], v[84:87]
	v_mfma_f32_16x16x32_f16 v[88:91], v[152:155], v[242:245], v[88:91]
	v_mfma_f32_16x16x32_f16 v[92:95], v[156:159], v[242:245], v[92:95]
	v_mfma_f32_16x16x32_f16 v[96:99], v[160:163], v[242:245], v[96:99]
	v_mfma_f32_16x16x32_f16 v[100:103], v[148:151], v[246:249], v[100:103]
	v_mfma_f32_16x16x32_f16 v[104:107], v[152:155], v[246:249], v[104:107]
	v_mfma_f32_16x16x32_f16 v[108:111], v[156:159], v[246:249], v[108:111]
	v_mfma_f32_16x16x32_f16 v[112:115], v[160:163], v[246:249], v[112:115]
	v_mfma_f32_16x16x32_f16 v[116:119], v[148:151], v[250:253], v[116:119]
	v_mfma_f32_16x16x32_f16 v[120:123], v[152:155], v[250:253], v[120:123]
	v_mfma_f32_16x16x32_f16 v[124:127], v[156:159], v[250:253], v[124:127]
	v_mfma_f32_16x16x32_f16 v[128:131], v[160:163], v[250:253], v[128:131]
	s_sub_u32 s77, s50, 0x1000
	s_lshr_b32 s77, s77, 12
	s_add_u32 s77, s77, 1
	s_cmp_lt_u32 s50, 0x1000
	s_cselect_b32 s77, 0, s77
	s_mul_i32 s77, s77, 0x6000
	s_add_u32 s68, s26, s77
	s_addc_u32 s69, s27, 0
	s_add_u32 s68, s68, 0x2000
	s_addc_u32 s69, s69, 0
	s_lshl_b32 s82, s50, 11
	s_add_u32 s80, s42, s82
	s_addc_u32 s81, s43, 0
	s_lshl_b32 s82, s37, 1
	s_add_u32 s80, s80, s82
	s_addc_u32 s81, s81, 0
	v_and_b32_e32 v172, 15, v200
	v_bfe_u32 v173, v200, 4, 2
	v_bfe_u32 v174, v200, 6, 2
	v_bfe_u32 v175, v200, 8, 1
	v_lshlrev_b32_e32 v176, 6, v174
	v_lshl_or_b32 v176, v173, 2, v176
	v_lshl_or_b32 v175, v175, 7, v172
	v_lshlrev_b32_e32 v175, 11, v175
	v_lshl_add_u32 v177, v176, 1, v175
	v_lshlrev_b32_e32 v178, 1, v175
	v_lshl_add_u32 v178, v176, 2, v178
	s_cmp_lt_u32 s50, 0x1000
	s_cselect_b32 s77, 0, 8
	s_load_dwordx2 s[28:29], s[22:23], s77
	s_sub_u32 s77, s50, 0x1000
	s_cselect_b32 s77, s50, s77
	s_lshl_b32 s77, s77, 12
	s_lshl_b32 s82, s37, 2
	s_add_u32 s77, s77, s82
	s_waitcnt lgkmcnt(0)
	s_add_u32 s28, s28, s77
	s_addc_u32 s29, s29, 0
	v_add_u32_e32 v176, s37, v176
	v_lshlrev_b32_e32 v176, 2, v176
	global_load_dwordx4 v[132:135], v176, s[68:69]
	global_load_dwordx4 v[136:139], v176, s[68:69] offset:64
	global_load_dwordx4 v[140:143], v176, s[68:69] offset:128
	global_load_dwordx4 v[144:147], v176, s[68:69] offset:192
	v_and_b32_e32 v172, 1, v173
	v_mul_u32_u24_e32 v172, 24, v172
	v_add_u32_e32 v177, v177, v172
	global_load_dwordx4 v[184:187], v178, s[28:29]
	global_load_dwordx4 v[188:191], v178, s[28:29] offset:64
	global_load_dwordx4 v[192:195], v178, s[28:29] offset:128
	global_load_dwordx4 v[196:199], v178, s[28:29] offset:192
	v_add_u32_e32 v178, 0x10000, v178
	global_load_dwordx4 v[238:241], v178, s[28:29]
	global_load_dwordx4 v[242:245], v178, s[28:29] offset:64
	global_load_dwordx4 v[246:249], v178, s[28:29] offset:128
	global_load_dwordx4 v[250:253], v178, s[28:29] offset:192
	s_waitcnt vmcnt(6)
	v_pk_mul_f32 v[184:185], v[184:185], s[84:85] op_sel_hi:[1,0]
	v_pk_mul_f32 v[186:187], v[186:187], s[84:85] op_sel_hi:[1,0]
	v_pk_fma_f32 v[4:5], v[4:5], v[132:133], v[184:185]
	v_pk_fma_f32 v[6:7], v[6:7], v[134:135], v[186:187]
	v_cvt_pk_f16_f32 v172, v4, v5
	v_cvt_pk_f16_f32 v173, v6, v7
	v_pk_mul_f32 v[188:189], v[188:189], s[84:85] op_sel_hi:[1,0]
	v_pk_mul_f32 v[190:191], v[190:191], s[84:85] op_sel_hi:[1,0]
	v_pk_fma_f32 v[8:9], v[8:9], v[136:137], v[188:189]
	v_pk_fma_f32 v[10:11], v[10:11], v[138:139], v[190:191]
	v_cvt_pk_f16_f32 v174, v8, v9
	v_cvt_pk_f16_f32 v175, v10, v11
	s_nop 1
	v_permlane16_swap_b32_e32 v172, v174
	v_permlane16_swap_b32_e32 v173, v175
	global_store_dwordx4 v177, v[172:175], s[80:81]
	s_waitcnt vmcnt(5)
	v_pk_mul_f32 v[192:193], v[192:193], s[84:85] op_sel_hi:[1,0]
	v_pk_mul_f32 v[194:195], v[194:195], s[84:85] op_sel_hi:[1,0]
	v_pk_fma_f32 v[12:13], v[12:13], v[140:141], v[192:193]
	v_pk_fma_f32 v[14:15], v[14:15], v[142:143], v[194:195]
	v_cvt_pk_f16_f32 v228, v12, v13
	v_cvt_pk_f16_f32 v229, v14, v15
	v_pk_mul_f32 v[196:197], v[196:197], s[84:85] op_sel_hi:[1,0]
	v_pk_mul_f32 v[198:199], v[198:199], s[84:85] op_sel_hi:[1,0]
	v_pk_fma_f32 v[16:17], v[16:17], v[144:145], v[196:197]
	v_pk_fma_f32 v[18:19], v[18:19], v[146:147], v[198:199]
	v_cvt_pk_f16_f32 v230, v16, v17
	v_cvt_pk_f16_f32 v231, v18, v19
	s_nop 1
	v_permlane16_swap_b32_e32 v228, v230
	v_permlane16_swap_b32_e32 v229, v231
	global_store_dwordx4 v177, v[228:231], s[80:81] offset:64
	v_add_u32_e32 v177, 0x8000, v177
	v_add_u32_e32 v178, 0x10000, v178
	global_load_dwordx4 v[184:187], v178, s[28:29]
	global_load_dwordx4 v[188:191], v178, s[28:29] offset:64
	global_load_dwordx4 v[192:195], v178, s[28:29] offset:128
	global_load_dwordx4 v[196:199], v178, s[28:29] offset:192
	s_waitcnt vmcnt(8)
	v_pk_mul_f32 v[238:239], v[238:239], s[84:85] op_sel_hi:[1,0]
	v_pk_mul_f32 v[240:241], v[240:241], s[84:85] op_sel_hi:[1,0]
	v_pk_fma_f32 v[20:21], v[20:21], v[132:133], v[238:239]
	v_pk_fma_f32 v[22:23], v[22:23], v[134:135], v[240:241]
	v_cvt_pk_f16_f32 v172, v20, v21
	v_cvt_pk_f16_f32 v173, v22, v23
	v_pk_mul_f32 v[242:243], v[242:243], s[84:85] op_sel_hi:[1,0]
	v_pk_mul_f32 v[244:245], v[244:245], s[84:85] op_sel_hi:[1,0]
	v_pk_fma_f32 v[24:25], v[24:25], v[136:137], v[242:243]
	v_pk_fma_f32 v[26:27], v[26:27], v[138:139], v[244:245]
	v_cvt_pk_f16_f32 v174, v24, v25
	v_cvt_pk_f16_f32 v175, v26, v27
	s_nop 1
	v_permlane16_swap_b32_e32 v172, v174
	v_permlane16_swap_b32_e32 v173, v175
	global_store_dwordx4 v177, v[172:175], s[80:81]
	s_waitcnt vmcnt(7)
	v_pk_mul_f32 v[246:247], v[246:247], s[84:85] op_sel_hi:[1,0]
	v_pk_mul_f32 v[248:249], v[248:249], s[84:85] op_sel_hi:[1,0]
	v_pk_fma_f32 v[28:29], v[28:29], v[140:141], v[246:247]
	v_pk_fma_f32 v[30:31], v[30:31], v[142:143], v[248:249]
	v_cvt_pk_f16_f32 v228, v28, v29
	v_cvt_pk_f16_f32 v229, v30, v31
	v_pk_mul_f32 v[250:251], v[250:251], s[84:85] op_sel_hi:[1,0]
	v_pk_mul_f32 v[252:253], v[252:253], s[84:85] op_sel_hi:[1,0]
	v_pk_fma_f32 v[32:33], v[32:33], v[144:145], v[250:251]
	v_pk_fma_f32 v[34:35], v[34:35], v[146:147], v[252:253]
	v_cvt_pk_f16_f32 v230, v32, v33
	v_cvt_pk_f16_f32 v231, v34, v35
	s_nop 1
	v_permlane16_swap_b32_e32 v228, v230
	v_permlane16_swap_b32_e32 v229, v231
	global_store_dwordx4 v177, v[228:231], s[80:81] offset:64
	v_add_u32_e32 v177, 0x8000, v177
	v_add_u32_e32 v178, 0x10000, v178
	global_load_dwordx4 v[238:241], v178, s[28:29]
	global_load_dwordx4 v[242:245], v178, s[28:29] offset:64
	global_load_dwordx4 v[246:249], v178, s[28:29] offset:128
	global_load_dwordx4 v[250:253], v178, s[28:29] offset:192
	s_waitcnt vmcnt(8)
	v_pk_mul_f32 v[184:185], v[184:185], s[84:85] op_sel_hi:[1,0]
	v_pk_mul_f32 v[186:187], v[186:187], s[84:85] op_sel_hi:[1,0]
	v_pk_fma_f32 v[36:37], v[36:37], v[132:133], v[184:185]
	v_pk_fma_f32 v[38:39], v[38:39], v[134:135], v[186:187]
	v_cvt_pk_f16_f32 v172, v36, v37
	v_cvt_pk_f16_f32 v173, v38, v39
	v_pk_mul_f32 v[188:189], v[188:189], s[84:85] op_sel_hi:[1,0]
	v_pk_mul_f32 v[190:191], v[190:191], s[84:85] op_sel_hi:[1,0]
	v_pk_fma_f32 v[40:41], v[40:41], v[136:137], v[188:189]
	v_pk_fma_f32 v[42:43], v[42:43], v[138:139], v[190:191]
	v_cvt_pk_f16_f32 v174, v40, v41
	v_cvt_pk_f16_f32 v175, v42, v43
	s_nop 1
	v_permlane16_swap_b32_e32 v172, v174
	v_permlane16_swap_b32_e32 v173, v175
	global_store_dwordx4 v177, v[172:175], s[80:81]
	s_waitcnt vmcnt(7)
	v_pk_mul_f32 v[192:193], v[192:193], s[84:85] op_sel_hi:[1,0]
	v_pk_mul_f32 v[194:195], v[194:195], s[84:85] op_sel_hi:[1,0]
	v_pk_fma_f32 v[44:45], v[44:45], v[140:141], v[192:193]
	v_pk_fma_f32 v[46:47], v[46:47], v[142:143], v[194:195]
	v_cvt_pk_f16_f32 v228, v44, v45
	v_cvt_pk_f16_f32 v229, v46, v47
	v_pk_mul_f32 v[196:197], v[196:197], s[84:85] op_sel_hi:[1,0]
	v_pk_mul_f32 v[198:199], v[198:199], s[84:85] op_sel_hi:[1,0]
	v_pk_fma_f32 v[48:49], v[48:49], v[144:145], v[196:197]
	v_pk_fma_f32 v[50:51], v[50:51], v[146:147], v[198:199]
	v_cvt_pk_f16_f32 v230, v48, v49
	v_cvt_pk_f16_f32 v231, v50, v51
	s_nop 1
	v_permlane16_swap_b32_e32 v228, v230
	v_permlane16_swap_b32_e32 v229, v231
	global_store_dwordx4 v177, v[228:231], s[80:81] offset:64
	v_add_u32_e32 v177, 0x8000, v177
	v_add_u32_e32 v178, 0x10000, v178
	global_load_dwordx4 v[184:187], v178, s[28:29]
	global_load_dwordx4 v[188:191], v178, s[28:29] offset:64
	global_load_dwordx4 v[192:195], v178, s[28:29] offset:128
	global_load_dwordx4 v[196:199], v178, s[28:29] offset:192
	s_waitcnt vmcnt(8)
	v_pk_mul_f32 v[238:239], v[238:239], s[84:85] op_sel_hi:[1,0]
	v_pk_mul_f32 v[240:241], v[240:241], s[84:85] op_sel_hi:[1,0]
	v_pk_fma_f32 v[52:53], v[52:53], v[132:133], v[238:239]
	v_pk_fma_f32 v[54:55], v[54:55], v[134:135], v[240:241]
	v_cvt_pk_f16_f32 v172, v52, v53
	v_cvt_pk_f16_f32 v173, v54, v55
	v_pk_mul_f32 v[242:243], v[242:243], s[84:85] op_sel_hi:[1,0]
	v_pk_mul_f32 v[244:245], v[244:245], s[84:85] op_sel_hi:[1,0]
	v_pk_fma_f32 v[56:57], v[56:57], v[136:137], v[242:243]
	v_pk_fma_f32 v[58:59], v[58:59], v[138:139], v[244:245]
	v_cvt_pk_f16_f32 v174, v56, v57
	v_cvt_pk_f16_f32 v175, v58, v59
	s_nop 1
	v_permlane16_swap_b32_e32 v172, v174
	v_permlane16_swap_b32_e32 v173, v175
	global_store_dwordx4 v177, v[172:175], s[80:81]
	s_waitcnt vmcnt(7)
	v_pk_mul_f32 v[246:247], v[246:247], s[84:85] op_sel_hi:[1,0]
	v_pk_mul_f32 v[248:249], v[248:249], s[84:85] op_sel_hi:[1,0]
	v_pk_fma_f32 v[60:61], v[60:61], v[140:141], v[246:247]
	v_pk_fma_f32 v[62:63], v[62:63], v[142:143], v[248:249]
	v_cvt_pk_f16_f32 v228, v60, v61
	v_cvt_pk_f16_f32 v229, v62, v63
	v_pk_mul_f32 v[250:251], v[250:251], s[84:85] op_sel_hi:[1,0]
	v_pk_mul_f32 v[252:253], v[252:253], s[84:85] op_sel_hi:[1,0]
	v_pk_fma_f32 v[64:65], v[64:65], v[144:145], v[250:251]
	v_pk_fma_f32 v[66:67], v[66:67], v[146:147], v[252:253]
	v_cvt_pk_f16_f32 v230, v64, v65
	v_cvt_pk_f16_f32 v231, v66, v67
	s_nop 1
	v_permlane16_swap_b32_e32 v228, v230
	v_permlane16_swap_b32_e32 v229, v231
	global_store_dwordx4 v177, v[228:231], s[80:81] offset:64
	v_add_u32_e32 v177, 0x8000, v177
	v_add_u32_e32 v178, 0x10000, v178
	global_load_dwordx4 v[238:241], v178, s[28:29]
	global_load_dwordx4 v[242:245], v178, s[28:29] offset:64
	global_load_dwordx4 v[246:249], v178, s[28:29] offset:128
	global_load_dwordx4 v[250:253], v178, s[28:29] offset:192
	s_waitcnt vmcnt(8)
	v_pk_mul_f32 v[184:185], v[184:185], s[84:85] op_sel_hi:[1,0]
	v_pk_mul_f32 v[186:187], v[186:187], s[84:85] op_sel_hi:[1,0]
	v_pk_fma_f32 v[68:69], v[68:69], v[132:133], v[184:185]
	v_pk_fma_f32 v[70:71], v[70:71], v[134:135], v[186:187]
	v_cvt_pk_f16_f32 v172, v68, v69
	v_cvt_pk_f16_f32 v173, v70, v71
	v_pk_mul_f32 v[188:189], v[188:189], s[84:85] op_sel_hi:[1,0]
	v_pk_mul_f32 v[190:191], v[190:191], s[84:85] op_sel_hi:[1,0]
	v_pk_fma_f32 v[72:73], v[72:73], v[136:137], v[188:189]
	v_pk_fma_f32 v[74:75], v[74:75], v[138:139], v[190:191]
	v_cvt_pk_f16_f32 v174, v72, v73
	v_cvt_pk_f16_f32 v175, v74, v75
	s_nop 1
	v_permlane16_swap_b32_e32 v172, v174
	v_permlane16_swap_b32_e32 v173, v175
	global_store_dwordx4 v177, v[172:175], s[80:81]
	s_waitcnt vmcnt(7)
	v_pk_mul_f32 v[192:193], v[192:193], s[84:85] op_sel_hi:[1,0]
	v_pk_mul_f32 v[194:195], v[194:195], s[84:85] op_sel_hi:[1,0]
	v_pk_fma_f32 v[76:77], v[76:77], v[140:141], v[192:193]
	v_pk_fma_f32 v[78:79], v[78:79], v[142:143], v[194:195]
	v_cvt_pk_f16_f32 v228, v76, v77
	v_cvt_pk_f16_f32 v229, v78, v79
	v_pk_mul_f32 v[196:197], v[196:197], s[84:85] op_sel_hi:[1,0]
	v_pk_mul_f32 v[198:199], v[198:199], s[84:85] op_sel_hi:[1,0]
	v_pk_fma_f32 v[80:81], v[80:81], v[144:145], v[196:197]
	v_pk_fma_f32 v[82:83], v[82:83], v[146:147], v[198:199]
	v_cvt_pk_f16_f32 v230, v80, v81
	v_cvt_pk_f16_f32 v231, v82, v83
	s_nop 1
	v_permlane16_swap_b32_e32 v228, v230
	v_permlane16_swap_b32_e32 v229, v231
	global_store_dwordx4 v177, v[228:231], s[80:81] offset:64
	v_add_u32_e32 v177, 0x8000, v177
	v_add_u32_e32 v178, 0x10000, v178
	global_load_dwordx4 v[184:187], v178, s[28:29]
	global_load_dwordx4 v[188:191], v178, s[28:29] offset:64
	global_load_dwordx4 v[192:195], v178, s[28:29] offset:128
	global_load_dwordx4 v[196:199], v178, s[28:29] offset:192
	s_waitcnt vmcnt(8)
	v_pk_mul_f32 v[238:239], v[238:239], s[84:85] op_sel_hi:[1,0]
	v_pk_mul_f32 v[240:241], v[240:241], s[84:85] op_sel_hi:[1,0]
	v_pk_fma_f32 v[84:85], v[84:85], v[132:133], v[238:239]
	v_pk_fma_f32 v[86:87], v[86:87], v[134:135], v[240:241]
	v_cvt_pk_f16_f32 v172, v84, v85
	v_cvt_pk_f16_f32 v173, v86, v87
	v_pk_mul_f32 v[242:243], v[242:243], s[84:85] op_sel_hi:[1,0]
	v_pk_mul_f32 v[244:245], v[244:245], s[84:85] op_sel_hi:[1,0]
	v_pk_fma_f32 v[88:89], v[88:89], v[136:137], v[242:243]
	v_pk_fma_f32 v[90:91], v[90:91], v[138:139], v[244:245]
	v_cvt_pk_f16_f32 v174, v88, v89
	v_cvt_pk_f16_f32 v175, v90, v91
	s_nop 1
	v_permlane16_swap_b32_e32 v172, v174
	v_permlane16_swap_b32_e32 v173, v175
	global_store_dwordx4 v177, v[172:175], s[80:81]
	s_waitcnt vmcnt(7)
	v_pk_mul_f32 v[246:247], v[246:247], s[84:85] op_sel_hi:[1,0]
	v_pk_mul_f32 v[248:249], v[248:249], s[84:85] op_sel_hi:[1,0]
	v_pk_fma_f32 v[92:93], v[92:93], v[140:141], v[246:247]
	v_pk_fma_f32 v[94:95], v[94:95], v[142:143], v[248:249]
	v_cvt_pk_f16_f32 v228, v92, v93
	v_cvt_pk_f16_f32 v229, v94, v95
	v_pk_mul_f32 v[250:251], v[250:251], s[84:85] op_sel_hi:[1,0]
	v_pk_mul_f32 v[252:253], v[252:253], s[84:85] op_sel_hi:[1,0]
	v_pk_fma_f32 v[96:97], v[96:97], v[144:145], v[250:251]
	v_pk_fma_f32 v[98:99], v[98:99], v[146:147], v[252:253]
	v_cvt_pk_f16_f32 v230, v96, v97
	v_cvt_pk_f16_f32 v231, v98, v99
	s_nop 1
	v_permlane16_swap_b32_e32 v228, v230
	v_permlane16_swap_b32_e32 v229, v231
	global_store_dwordx4 v177, v[228:231], s[80:81] offset:64
	v_add_u32_e32 v177, 0x8000, v177
	v_add_u32_e32 v178, 0x10000, v178
	global_load_dwordx4 v[238:241], v178, s[28:29]
	global_load_dwordx4 v[242:245], v178, s[28:29] offset:64
	global_load_dwordx4 v[246:249], v178, s[28:29] offset:128
	global_load_dwordx4 v[250:253], v178, s[28:29] offset:192
	s_waitcnt vmcnt(8)
	v_pk_mul_f32 v[184:185], v[184:185], s[84:85] op_sel_hi:[1,0]
	v_pk_mul_f32 v[186:187], v[186:187], s[84:85] op_sel_hi:[1,0]
	v_pk_fma_f32 v[100:101], v[100:101], v[132:133], v[184:185]
	v_pk_fma_f32 v[102:103], v[102:103], v[134:135], v[186:187]
	v_cvt_pk_f16_f32 v172, v100, v101
	v_cvt_pk_f16_f32 v173, v102, v103
	v_pk_mul_f32 v[188:189], v[188:189], s[84:85] op_sel_hi:[1,0]
	v_pk_mul_f32 v[190:191], v[190:191], s[84:85] op_sel_hi:[1,0]
	v_pk_fma_f32 v[104:105], v[104:105], v[136:137], v[188:189]
	v_pk_fma_f32 v[106:107], v[106:107], v[138:139], v[190:191]
	v_cvt_pk_f16_f32 v174, v104, v105
	v_cvt_pk_f16_f32 v175, v106, v107
	s_nop 1
	v_permlane16_swap_b32_e32 v172, v174
	v_permlane16_swap_b32_e32 v173, v175
	global_store_dwordx4 v177, v[172:175], s[80:81]
	s_waitcnt vmcnt(7)
	v_pk_mul_f32 v[192:193], v[192:193], s[84:85] op_sel_hi:[1,0]
	v_pk_mul_f32 v[194:195], v[194:195], s[84:85] op_sel_hi:[1,0]
	v_pk_fma_f32 v[108:109], v[108:109], v[140:141], v[192:193]
	v_pk_fma_f32 v[110:111], v[110:111], v[142:143], v[194:195]
	v_cvt_pk_f16_f32 v228, v108, v109
	v_cvt_pk_f16_f32 v229, v110, v111
	v_pk_mul_f32 v[196:197], v[196:197], s[84:85] op_sel_hi:[1,0]
	v_pk_mul_f32 v[198:199], v[198:199], s[84:85] op_sel_hi:[1,0]
	v_pk_fma_f32 v[112:113], v[112:113], v[144:145], v[196:197]
	v_pk_fma_f32 v[114:115], v[114:115], v[146:147], v[198:199]
	v_cvt_pk_f16_f32 v230, v112, v113
	v_cvt_pk_f16_f32 v231, v114, v115
	s_nop 1
	v_permlane16_swap_b32_e32 v228, v230
	v_permlane16_swap_b32_e32 v229, v231
	global_store_dwordx4 v177, v[228:231], s[80:81] offset:64
	v_add_u32_e32 v177, 0x8000, v177
	s_waitcnt vmcnt(4)
	v_pk_mul_f32 v[238:239], v[238:239], s[84:85] op_sel_hi:[1,0]
	v_pk_mul_f32 v[240:241], v[240:241], s[84:85] op_sel_hi:[1,0]
	v_pk_fma_f32 v[116:117], v[116:117], v[132:133], v[238:239]
	v_pk_fma_f32 v[118:119], v[118:119], v[134:135], v[240:241]
	v_cvt_pk_f16_f32 v172, v116, v117
	v_cvt_pk_f16_f32 v173, v118, v119
	v_pk_mul_f32 v[242:243], v[242:243], s[84:85] op_sel_hi:[1,0]
	v_pk_mul_f32 v[244:245], v[244:245], s[84:85] op_sel_hi:[1,0]
	v_pk_fma_f32 v[120:121], v[120:121], v[136:137], v[242:243]
	v_pk_fma_f32 v[122:123], v[122:123], v[138:139], v[244:245]
	v_cvt_pk_f16_f32 v174, v120, v121
	v_cvt_pk_f16_f32 v175, v122, v123
	s_nop 1
	v_permlane16_swap_b32_e32 v172, v174
	v_permlane16_swap_b32_e32 v173, v175
	global_store_dwordx4 v177, v[172:175], s[80:81]
	s_waitcnt vmcnt(3)
	v_pk_mul_f32 v[246:247], v[246:247], s[84:85] op_sel_hi:[1,0]
	v_pk_mul_f32 v[248:249], v[248:249], s[84:85] op_sel_hi:[1,0]
	v_pk_fma_f32 v[124:125], v[124:125], v[140:141], v[246:247]
	v_pk_fma_f32 v[126:127], v[126:127], v[142:143], v[248:249]
	v_cvt_pk_f16_f32 v228, v124, v125
	v_cvt_pk_f16_f32 v229, v126, v127
	v_pk_mul_f32 v[250:251], v[250:251], s[84:85] op_sel_hi:[1,0]
	v_pk_mul_f32 v[252:253], v[252:253], s[84:85] op_sel_hi:[1,0]
	v_pk_fma_f32 v[128:129], v[128:129], v[144:145], v[250:251]
	v_pk_fma_f32 v[130:131], v[130:131], v[146:147], v[252:253]
	v_cvt_pk_f16_f32 v230, v128, v129
	v_cvt_pk_f16_f32 v231, v130, v131
	s_nop 1
	v_permlane16_swap_b32_e32 v228, v230
	v_permlane16_swap_b32_e32 v229, v231
	global_store_dwordx4 v177, v[228:231], s[80:81] offset:64
	s_nop 1
	s_branch .LBB0_1289
